# GEMM loops: first K-tile of each unit peeled so first-touch MFMAs take C=0; the 128-instruction accumulator zeroing pass per tile removed
# speedup vs baseline: 1.0181x; 1.0181x over previous
; #define PG8_STAGE(bufoff, gbase, voff) do { _Pragma("unroll") for (int _i = 0; _i < 2; ++_i) \
;         __builtin_amdgcn_global_load_lds((const unsigned*)((const char*)(gbase) + (voff)[_i]), (PG8_LAS unsigned*)(lds + (bufoff) + ldsw + _i * 8192), 16, 0, 0); } while (0)
; #define PG8_LDA(dst, b, h) do { _Pragma("unroll") for (int m = 0; m < 4; ++m) _Pragma("unroll") for (int k = 0; k < 2; ++k) dst[m][k] = *(const PG8_LAS bf16x8*)(lds + PG8_SA(b, h) + aoff + m * 2048 + k * 1024); } while (0)
; #define PG8_LDB(dst, b, h) do { _Pragma("unroll") for (int n = 0; n < 2; ++n) _Pragma("unroll") for (int k = 0; k < 2; ++k) dst[n][k] = *(const PG8_LAS bf16x8*)(lds + PG8_SB(b, h) + boff + n * 2048 + k * 1024); } while (0)
; #define PG8_WAIT_V(n) asm volatile("s_waitcnt vmcnt(" #n ")" ::: "memory")
; #define PG8_WAIT_L(n) asm volatile("s_waitcnt lgkmcnt(" #n ")" ::: "memory")
; #define PG8_BAR __builtin_amdgcn_s_barrier()
; template <class Epi, class Sched, bool ALIGN_EPI = false, bool SP2 = false>
; __device__ __forceinline__ void gemm_phase(PG8_LAS unsigned char* lds, const Gemm g, const Sched& S, const Epi& E) {
;     ...
;     for (;;) {
;         const bool has_next = S.next(ui + 1, nxt);
;         const char* nA = has_next ? (const char*)g.A + (size_t)nxt.pm * tstep : cA; const char* nB = has_next ? (const char*)g.Bt + (size_t)nxt.pn * tstep : cB;
;         for (int t = 0; t < nt; t += 2) {
;             const bool last = (t == nt - 2);
;             const char* a1 = cA + (size_t)(t + 1) * kstep;
;             const char* a2 = last ? nA : cA + (size_t)(t + 2) * kstep; const char* b2 = last ? nB : cB + (size_t)(t + 2) * kstep;
;             const char* a3 = a2 + kstep; const char* b3 = b2 + kstep;
;             if (last && has_next) S.a_ready(nxt);
;             if (last) E.pre(cur, wr, fr, rsv);
;             if constexpr (SP2) {
;             PG8_LDB(B0, 0, 0); PG8_LDB(B1, 0, 1); PG8_SCHED; PG8_LDA(At, 0, 0); PG8_STAGE(PG8_SA(1, 1), a1 + hstep, voffA);
;             PG8_WAIT_V(8); PG8_WAIT_L(0); PG8_BAR; PG8_MMA(0, 0, At, B0); PG8_MMA(0, 1, At, B1); PG8_BAR; PG8_SCHED;
;             PG8_LDA(At, 0, 1); PG8_STAGE(PG8_SB(0, 0), b2, voffB); PG8_STAGE(PG8_SB(0, 1), b2 + hstep, voffB); PG8_STAGE(PG8_SA(0, 0), a2, voffA);
;             PG8_WAIT_V(8); PG8_WAIT_L(0); PG8_BAR; PG8_MMA(1, 0, At, B0); PG8_MMA(1, 1, At, B1); PG8_BAR; PG8_SCHED;
.LBB0_127:
	s_ashr_i32 s13, s12, 31
	s_lshl_b64 s[14:15], s[12:13], 19
	s_add_u32 s14, s28, s14
	s_addc_u32 s15, s29, s15
	s_and_b64 s[20:21], s[4:5], exec
	s_cselect_b32 s13, s15, s1
	s_cselect_b32 s36, s14, s0
	s_ashr_i32 s11, s10, 31
	s_lshl_b64 s[20:21], s[10:11], 19
	s_add_u32 s20, s16, s20
	s_addc_u32 s21, s19, s21
	s_and_b64 s[38:39], s[4:5], exec
	s_cselect_b32 s11, s21, s23
	s_cselect_b32 s37, s20, s22
	s_add_u32 s0, s0, 0x40080
	v_lshl_add_u32 v144, s24, 8, v152
	s_addc_u32 s1, s1, 0
	v_ashrrev_i32_e32 v145, 31, v144
	s_add_u32 s38, s22, 0x100
	v_lshl_add_u64 v[146:147], v[144:145], 2, s[72:73]
	s_addc_u32 s39, s23, 0
	s_mov_b32 s40, -2
	s_waitcnt vmcnt(0)
	s_branch .LBB0_129
.LpeelA:
	s_add_u32 s24, s0, 0xfffc0080
	s_addc_u32 s25, s1, -1
	s_and_b64 s[22:23], s[22:23], exec
	s_cselect_b32 s25, s13, s25
	s_cselect_b32 s24, s36, s24
	s_cselect_b32 s23, s11, s39
	s_cselect_b32 s22, s37, s38
	s_add_i32 s41, 0, 0x10000
	v_add_u32_e32 v145, s41, v153
	s_add_i32 s46, 0, 0x14000
	ds_read_b128 v[148:151], v145
	ds_read_b128 v[172:175], v145 offset:1024
	ds_read_b128 v[176:179], v145 offset:2048
	ds_read_b128 v[180:183], v145 offset:3072
	v_add_u32_e32 v145, s46, v153
	ds_read_b128 v[184:187], v145
	ds_read_b128 v[188:191], v145 offset:1024
	ds_read_b128 v[192:195], v145 offset:2048
	ds_read_b128 v[196:199], v145 offset:3072
	v_lshl_add_u64 v[248:249], s[0:1], 0, v[140:141]
	s_add_i32 m0, s34, 0xc000
	ds_read_b128 v[200:203], v162
	ds_read_b128 v[204:207], v162 offset:1024
	ds_read_b128 v[208:211], v162 offset:2048
	ds_read_b128 v[212:215], v162 offset:3072
	ds_read_b128 v[216:219], v162 offset:4096
	ds_read_b128 v[236:239], v162 offset:5120
	ds_read_b128 v[240:243], v162 offset:6144
	ds_read_b128 v[244:247], v162 offset:7168
	global_load_lds_dwordx4 v[248:249], off
	v_lshl_add_u64 v[248:249], s[0:1], 0, v[142:143]
	s_add_i32 m0, s34, 0xe000
	s_nop 0
	global_load_lds_dwordx4 v[248:249], off
	s_waitcnt vmcnt(8)
	s_waitcnt lgkmcnt(0)
	s_barrier
	s_setprio 1
	s_waitcnt lgkmcnt(0)
	v_mfma_f32_16x16x32_bf16 v[130:133], v[148:151], v[200:203], 0
	v_mfma_f32_16x16x32_bf16 v[126:129], v[176:179], v[200:203], 0
	v_mfma_f32_16x16x32_bf16 v[114:117], v[148:151], v[208:211], 0
	v_mfma_f32_16x16x32_bf16 v[110:113], v[176:179], v[208:211], 0
	v_mfma_f32_16x16x32_bf16 v[98:101], v[148:151], v[216:219], 0
	v_mfma_f32_16x16x32_bf16 v[94:97], v[176:179], v[216:219], 0
	v_mfma_f32_16x16x32_bf16 v[82:85], v[148:151], v[240:243], 0
	v_mfma_f32_16x16x32_bf16 v[78:81], v[176:179], v[240:243], 0
	v_mfma_f32_16x16x32_bf16 v[130:133], v[172:175], v[204:207], v[130:133]
	v_mfma_f32_16x16x32_bf16 v[126:129], v[180:183], v[204:207], v[126:129]
	v_mfma_f32_16x16x32_bf16 v[114:117], v[172:175], v[212:215], v[114:117]
	v_mfma_f32_16x16x32_bf16 v[110:113], v[180:183], v[212:215], v[110:113]
	v_mfma_f32_16x16x32_bf16 v[98:101], v[172:175], v[236:239], v[98:101]
	v_mfma_f32_16x16x32_bf16 v[94:97], v[180:183], v[236:239], v[94:97]
	v_mfma_f32_16x16x32_bf16 v[82:85], v[172:175], v[244:247], v[82:85]
	v_mfma_f32_16x16x32_bf16 v[78:81], v[180:183], v[244:247], v[78:81]
	s_setprio 0
	s_setprio 1
	v_mfma_f32_16x16x32_bf16 v[122:125], v[184:187], v[200:203], 0
	v_mfma_f32_16x16x32_bf16 v[118:121], v[192:195], v[200:203], 0
	v_mfma_f32_16x16x32_bf16 v[106:109], v[184:187], v[208:211], 0
	v_mfma_f32_16x16x32_bf16 v[102:105], v[192:195], v[208:211], 0
	v_mfma_f32_16x16x32_bf16 v[90:93], v[184:187], v[216:219], 0
	v_mfma_f32_16x16x32_bf16 v[86:89], v[192:195], v[216:219], 0
	v_mfma_f32_16x16x32_bf16 v[74:77], v[184:187], v[240:243], 0
	v_mfma_f32_16x16x32_bf16 v[70:73], v[192:195], v[240:243], 0
	v_mfma_f32_16x16x32_bf16 v[122:125], v[188:191], v[204:207], v[122:125]
	v_mfma_f32_16x16x32_bf16 v[118:121], v[196:199], v[204:207], v[118:121]
	v_mfma_f32_16x16x32_bf16 v[106:109], v[188:191], v[212:215], v[106:109]
	v_mfma_f32_16x16x32_bf16 v[102:105], v[196:199], v[212:215], v[102:105]
	v_mfma_f32_16x16x32_bf16 v[90:93], v[188:191], v[236:239], v[90:93]
	v_mfma_f32_16x16x32_bf16 v[86:89], v[196:199], v[236:239], v[86:89]
	v_mfma_f32_16x16x32_bf16 v[74:77], v[188:191], v[244:247], v[74:77]
	v_mfma_f32_16x16x32_bf16 v[70:73], v[196:199], v[244:247], v[70:73]
	s_setprio 0
	s_barrier
	s_add_i32 s41, s41, s33
	v_lshl_add_u64 v[248:249], s[22:23], 0, v[156:157]
	s_mov_b32 m0, s41
	ds_read_b128 v[200:203], v162 offset:16384
	ds_read_b128 v[204:207], v162 offset:17408
	ds_read_b128 v[208:211], v162 offset:18432
	ds_read_b128 v[212:215], v162 offset:19456
	ds_read_b128 v[216:219], v162 offset:20480
	ds_read_b128 v[236:239], v162 offset:21504
	ds_read_b128 v[240:243], v162 offset:22528
	ds_read_b128 v[244:247], v162 offset:23552
	global_load_lds_dwordx4 v[248:249], off
	s_add_i32 m0, s41, 0x2000
	s_add_u32 s44, s22, 0x40000
	v_lshl_add_u64 v[250:251], s[22:23], 0, v[134:135]
	s_addc_u32 s45, s23, 0
	s_add_i32 s41, s46, s33
	global_load_lds_dwordx4 v[250:251], off
	v_lshl_add_u64 v[226:227], s[44:45], 0, v[156:157]
	s_mov_b32 m0, s41
	v_lshl_add_u64 v[222:223], s[24:25], 0, v[136:137]
	global_load_lds_dwordx4 v[226:227], off
	v_lshl_add_u64 v[226:227], s[44:45], 0, v[134:135]
	s_add_i32 m0, s41, 0x2000
	s_nop 0
	global_load_lds_dwordx4 v[226:227], off
	v_lshl_add_u64 v[226:227], s[24:25], 0, v[138:139]
	s_mov_b32 m0, s34
	s_nop 0
	global_load_lds_dwordx4 v[226:227], off
	s_mov_b32 m0, s35
	s_nop 0
	global_load_lds_dwordx4 v[222:223], off
	s_waitcnt vmcnt(8)
	s_waitcnt lgkmcnt(0)
	s_barrier
; #define PG8_STAGE(bufoff, gbase, voff) do { _Pragma("unroll") for (int _i = 0; _i < 2; ++_i) \
;         __builtin_amdgcn_global_load_lds((const unsigned*)((const char*)(gbase) + (voff)[_i]), (PG8_LAS unsigned*)(lds + (bufoff) + ldsw + _i * 8192), 16, 0, 0); } while (0)
; #define PG8_LDA(dst, b, h) do { _Pragma("unroll") for (int m = 0; m < 4; ++m) _Pragma("unroll") for (int k = 0; k < 2; ++k) dst[m][k] = *(const PG8_LAS bf16x8*)(lds + PG8_SA(b, h) + aoff + m * 2048 + k * 1024); } while (0)
; #define PG8_LDB(dst, b, h) do { _Pragma("unroll") for (int n = 0; n < 2; ++n) _Pragma("unroll") for (int k = 0; k < 2; ++k) dst[n][k] = *(const PG8_LAS bf16x8*)(lds + PG8_SB(b, h) + boff + n * 2048 + k * 1024); } while (0)
; #define PG8_MMA(ai, bj, At, Bt) do { __builtin_amdgcn_s_setprio(1); _Pragma("unroll") for (int m = 0; m < 4; ++m) _Pragma("unroll") for (int n = 0; n < 2; ++n) _Pragma("unroll") for (int k = 0; k < 2; ++k) \
;         acc[ai][bj][m][n] = __builtin_amdgcn_mfma_f32_16x16x32_bf16(Bt[n][k], At[m][k], acc[ai][bj][m][n], 0, 0, 0); __builtin_amdgcn_s_setprio(0); } while (0)
; #define PG8_WAIT_V(n) asm volatile("s_waitcnt vmcnt(" #n ")" ::: "memory")
; #define PG8_WAIT_L(n) asm volatile("s_waitcnt lgkmcnt(" #n ")" ::: "memory")
; #define PG8_BAR __builtin_amdgcn_s_barrier()
; #define PG8_SCHED __builtin_amdgcn_sched_barrier(0)
; template <class Epi, class Sched, bool ALIGN_EPI = false, bool SP2 = false>
; __device__ __forceinline__ void gemm_phase(PG8_LAS unsigned char* lds, const Gemm g, const Sched& S, const Epi& E) {
;     ...
;             PG8_LDB(B0, 0, 0); PG8_LDB(B1, 0, 1); PG8_SCHED; PG8_LDA(At, 0, 0); PG8_STAGE(PG8_SA(1, 1), a1 + hstep, voffA);
;             PG8_WAIT_V(8); PG8_WAIT_L(0); PG8_BAR; PG8_MMA(0, 0, At, B0); PG8_MMA(0, 1, At, B1); PG8_BAR; PG8_SCHED;
;             PG8_LDA(At, 0, 1); PG8_STAGE(PG8_SB(0, 0), b2, voffB); PG8_STAGE(PG8_SB(0, 1), b2 + hstep, voffB); PG8_STAGE(PG8_SA(0, 0), a2, voffA);
;             PG8_WAIT_V(8); PG8_WAIT_L(0); PG8_BAR; PG8_MMA(1, 0, At, B0); PG8_MMA(1, 1, At, B1); PG8_BAR; PG8_SCHED;
	s_setprio 1
	s_waitcnt lgkmcnt(0)
	v_mfma_f32_16x16x32_bf16 v[66:69], v[148:151], v[200:203], 0
	v_mfma_f32_16x16x32_bf16 v[62:65], v[176:179], v[200:203], 0
	v_mfma_f32_16x16x32_bf16 v[50:53], v[148:151], v[208:211], 0
	v_mfma_f32_16x16x32_bf16 v[46:49], v[176:179], v[208:211], 0
	v_mfma_f32_16x16x32_bf16 v[34:37], v[148:151], v[216:219], 0
	v_mfma_f32_16x16x32_bf16 v[30:33], v[176:179], v[216:219], 0
	v_mfma_f32_16x16x32_bf16 v[18:21], v[148:151], v[240:243], 0
	v_mfma_f32_16x16x32_bf16 v[14:17], v[176:179], v[240:243], 0
	v_mfma_f32_16x16x32_bf16 v[66:69], v[172:175], v[204:207], v[66:69]
	v_mfma_f32_16x16x32_bf16 v[62:65], v[180:183], v[204:207], v[62:65]
	v_mfma_f32_16x16x32_bf16 v[50:53], v[172:175], v[212:215], v[50:53]
	v_mfma_f32_16x16x32_bf16 v[46:49], v[180:183], v[212:215], v[46:49]
	v_mfma_f32_16x16x32_bf16 v[34:37], v[172:175], v[236:239], v[34:37]
	v_mfma_f32_16x16x32_bf16 v[30:33], v[180:183], v[236:239], v[30:33]
	v_mfma_f32_16x16x32_bf16 v[18:21], v[172:175], v[244:247], v[18:21]
	v_mfma_f32_16x16x32_bf16 v[14:17], v[180:183], v[244:247], v[14:17]
	s_setprio 0
	s_setprio 1
	v_mfma_f32_16x16x32_bf16 v[58:61], v[184:187], v[200:203], 0
	v_mfma_f32_16x16x32_bf16 v[54:57], v[192:195], v[200:203], 0
	v_mfma_f32_16x16x32_bf16 v[42:45], v[184:187], v[208:211], 0
	v_mfma_f32_16x16x32_bf16 v[38:41], v[192:195], v[208:211], 0
	v_mfma_f32_16x16x32_bf16 v[26:29], v[184:187], v[216:219], 0
	v_mfma_f32_16x16x32_bf16 v[22:25], v[192:195], v[216:219], 0
	v_mfma_f32_16x16x32_bf16 v[10:13], v[184:187], v[240:243], 0
	v_mfma_f32_16x16x32_bf16 v[6:9], v[192:195], v[240:243], 0
	v_mfma_f32_16x16x32_bf16 v[58:61], v[188:191], v[204:207], v[58:61]
	v_mfma_f32_16x16x32_bf16 v[54:57], v[196:199], v[204:207], v[54:57]
	v_mfma_f32_16x16x32_bf16 v[42:45], v[188:191], v[212:215], v[42:45]
	v_mfma_f32_16x16x32_bf16 v[38:41], v[196:199], v[212:215], v[38:41]
	v_mfma_f32_16x16x32_bf16 v[26:29], v[188:191], v[236:239], v[26:29]
	v_mfma_f32_16x16x32_bf16 v[22:25], v[196:199], v[236:239], v[22:25]
	v_mfma_f32_16x16x32_bf16 v[10:13], v[188:191], v[244:247], v[10:13]
	v_mfma_f32_16x16x32_bf16 v[6:9], v[196:199], v[244:247], v[6:9]
	s_setprio 0
	s_barrier
	s_branch .LpeelA_mid
.LBB0_128:
	s_cmp_eq_u32 s40, -2
	s_cbranch_scc1 .LpeelA
	s_add_u32 s24, s0, 0xfffc0080
	s_addc_u32 s25, s1, -1
	s_and_b64 s[22:23], s[22:23], exec
	s_cselect_b32 s25, s13, s25
	s_cselect_b32 s24, s36, s24
	s_cselect_b32 s23, s11, s39
	s_cselect_b32 s22, s37, s38
	s_add_i32 s41, 0, 0x10000
	v_add_u32_e32 v145, s41, v153
	s_add_i32 s46, 0, 0x14000
	ds_read_b128 v[148:151], v145
	ds_read_b128 v[172:175], v145 offset:1024
	ds_read_b128 v[176:179], v145 offset:2048
	ds_read_b128 v[180:183], v145 offset:3072
	v_add_u32_e32 v145, s46, v153
	ds_read_b128 v[184:187], v145
	ds_read_b128 v[188:191], v145 offset:1024
	ds_read_b128 v[192:195], v145 offset:2048
	ds_read_b128 v[196:199], v145 offset:3072
	v_lshl_add_u64 v[248:249], s[0:1], 0, v[140:141]
	s_add_i32 m0, s34, 0xc000
	ds_read_b128 v[200:203], v162
	ds_read_b128 v[204:207], v162 offset:1024
	ds_read_b128 v[208:211], v162 offset:2048
	ds_read_b128 v[212:215], v162 offset:3072
	ds_read_b128 v[216:219], v162 offset:4096
	ds_read_b128 v[236:239], v162 offset:5120
	ds_read_b128 v[240:243], v162 offset:6144
	ds_read_b128 v[244:247], v162 offset:7168
	global_load_lds_dwordx4 v[248:249], off
	v_lshl_add_u64 v[248:249], s[0:1], 0, v[142:143]
	s_add_i32 m0, s34, 0xe000
	s_nop 0
	global_load_lds_dwordx4 v[248:249], off
	s_waitcnt vmcnt(8)
	s_waitcnt lgkmcnt(0)
	s_barrier
	s_setprio 1
	s_waitcnt lgkmcnt(0)
	v_mfma_f32_16x16x32_bf16 v[130:133], v[148:151], v[200:203], v[130:133]
	v_mfma_f32_16x16x32_bf16 v[126:129], v[176:179], v[200:203], v[126:129]
	v_mfma_f32_16x16x32_bf16 v[114:117], v[148:151], v[208:211], v[114:117]
	v_mfma_f32_16x16x32_bf16 v[110:113], v[176:179], v[208:211], v[110:113]
	v_mfma_f32_16x16x32_bf16 v[98:101], v[148:151], v[216:219], v[98:101]
	v_mfma_f32_16x16x32_bf16 v[94:97], v[176:179], v[216:219], v[94:97]
	v_mfma_f32_16x16x32_bf16 v[82:85], v[148:151], v[240:243], v[82:85]
	v_mfma_f32_16x16x32_bf16 v[78:81], v[176:179], v[240:243], v[78:81]
	v_mfma_f32_16x16x32_bf16 v[130:133], v[172:175], v[204:207], v[130:133]
	v_mfma_f32_16x16x32_bf16 v[126:129], v[180:183], v[204:207], v[126:129]
	v_mfma_f32_16x16x32_bf16 v[114:117], v[172:175], v[212:215], v[114:117]
	v_mfma_f32_16x16x32_bf16 v[110:113], v[180:183], v[212:215], v[110:113]
	v_mfma_f32_16x16x32_bf16 v[98:101], v[172:175], v[236:239], v[98:101]
	v_mfma_f32_16x16x32_bf16 v[94:97], v[180:183], v[236:239], v[94:97]
	v_mfma_f32_16x16x32_bf16 v[82:85], v[172:175], v[244:247], v[82:85]
	v_mfma_f32_16x16x32_bf16 v[78:81], v[180:183], v[244:247], v[78:81]
	s_setprio 0
	s_setprio 1
	v_mfma_f32_16x16x32_bf16 v[122:125], v[184:187], v[200:203], v[122:125]
	v_mfma_f32_16x16x32_bf16 v[118:121], v[192:195], v[200:203], v[118:121]
	v_mfma_f32_16x16x32_bf16 v[106:109], v[184:187], v[208:211], v[106:109]
	v_mfma_f32_16x16x32_bf16 v[102:105], v[192:195], v[208:211], v[102:105]
	v_mfma_f32_16x16x32_bf16 v[90:93], v[184:187], v[216:219], v[90:93]
	v_mfma_f32_16x16x32_bf16 v[86:89], v[192:195], v[216:219], v[86:89]
	v_mfma_f32_16x16x32_bf16 v[74:77], v[184:187], v[240:243], v[74:77]
	v_mfma_f32_16x16x32_bf16 v[70:73], v[192:195], v[240:243], v[70:73]
	v_mfma_f32_16x16x32_bf16 v[122:125], v[188:191], v[204:207], v[122:125]
	v_mfma_f32_16x16x32_bf16 v[118:121], v[196:199], v[204:207], v[118:121]
	v_mfma_f32_16x16x32_bf16 v[106:109], v[188:191], v[212:215], v[106:109]
	v_mfma_f32_16x16x32_bf16 v[102:105], v[196:199], v[212:215], v[102:105]
	v_mfma_f32_16x16x32_bf16 v[90:93], v[188:191], v[236:239], v[90:93]
	v_mfma_f32_16x16x32_bf16 v[86:89], v[196:199], v[236:239], v[86:89]
	v_mfma_f32_16x16x32_bf16 v[74:77], v[188:191], v[244:247], v[74:77]
	v_mfma_f32_16x16x32_bf16 v[70:73], v[196:199], v[244:247], v[70:73]
	s_setprio 0
	s_barrier
; #define PG8_STAGE(bufoff, gbase, voff) do { _Pragma("unroll") for (int _i = 0; _i < 2; ++_i) \
;         __builtin_amdgcn_global_load_lds((const unsigned*)((const char*)(gbase) + (voff)[_i]), (PG8_LAS unsigned*)(lds + (bufoff) + ldsw + _i * 8192), 16, 0, 0); } while (0)
; #define PG8_LDA(dst, b, h) do { _Pragma("unroll") for (int m = 0; m < 4; ++m) _Pragma("unroll") for (int k = 0; k < 2; ++k) dst[m][k] = *(const PG8_LAS bf16x8*)(lds + PG8_SA(b, h) + aoff + m * 2048 + k * 1024); } while (0)
; #define PG8_LDB(dst, b, h) do { _Pragma("unroll") for (int n = 0; n < 2; ++n) _Pragma("unroll") for (int k = 0; k < 2; ++k) dst[n][k] = *(const PG8_LAS bf16x8*)(lds + PG8_SB(b, h) + boff + n * 2048 + k * 1024); } while (0)
; #define PG8_MMA(ai, bj, At, Bt) do { __builtin_amdgcn_s_setprio(1); _Pragma("unroll") for (int m = 0; m < 4; ++m) _Pragma("unroll") for (int n = 0; n < 2; ++n) _Pragma("unroll") for (int k = 0; k < 2; ++k) \
;         acc[ai][bj][m][n] = __builtin_amdgcn_mfma_f32_16x16x32_bf16(Bt[n][k], At[m][k], acc[ai][bj][m][n], 0, 0, 0); __builtin_amdgcn_s_setprio(0); } while (0)
; #define PG8_WAIT_V(n) asm volatile("s_waitcnt vmcnt(" #n ")" ::: "memory")
; #define PG8_WAIT_L(n) asm volatile("s_waitcnt lgkmcnt(" #n ")" ::: "memory")
; #define PG8_BAR __builtin_amdgcn_s_barrier()
; #define PG8_SCHED __builtin_amdgcn_sched_barrier(0)
; template <class Epi, class Sched, bool ALIGN_EPI = false, bool SP2 = false>
; __device__ __forceinline__ void gemm_phase(PG8_LAS unsigned char* lds, const Gemm g, const Sched& S, const Epi& E) {
;     ...
;             PG8_LDA(At, 0, 1); PG8_STAGE(PG8_SB(0, 0), b2, voffB); PG8_STAGE(PG8_SB(0, 1), b2 + hstep, voffB); PG8_STAGE(PG8_SA(0, 0), a2, voffA);
;             PG8_WAIT_V(8); PG8_WAIT_L(0); PG8_BAR; PG8_MMA(1, 0, At, B0); PG8_MMA(1, 1, At, B1); PG8_BAR; PG8_SCHED;
;             PG8_LDB(B0, 1, 0); PG8_LDB(B1, 1, 1); PG8_SCHED; PG8_LDA(At, 1, 0); PG8_STAGE(PG8_SA(0, 1), a2 + hstep, voffA);
;             PG8_WAIT_V(8); PG8_WAIT_L(0); PG8_BAR; PG8_MMA(0, 0, At, B0); PG8_MMA(0, 1, At, B1); PG8_BAR; PG8_SCHED;
	s_add_i32 s41, s41, s33
	v_lshl_add_u64 v[248:249], s[22:23], 0, v[156:157]
	s_mov_b32 m0, s41
	ds_read_b128 v[200:203], v162 offset:16384
	ds_read_b128 v[204:207], v162 offset:17408
	ds_read_b128 v[208:211], v162 offset:18432
	ds_read_b128 v[212:215], v162 offset:19456
	ds_read_b128 v[216:219], v162 offset:20480
	ds_read_b128 v[236:239], v162 offset:21504
	ds_read_b128 v[240:243], v162 offset:22528
	ds_read_b128 v[244:247], v162 offset:23552
	global_load_lds_dwordx4 v[248:249], off
	s_add_i32 m0, s41, 0x2000
	s_add_u32 s44, s22, 0x40000
	v_lshl_add_u64 v[250:251], s[22:23], 0, v[134:135]
	s_addc_u32 s45, s23, 0
	s_add_i32 s41, s46, s33
	global_load_lds_dwordx4 v[250:251], off
	v_lshl_add_u64 v[226:227], s[44:45], 0, v[156:157]
	s_mov_b32 m0, s41
	v_lshl_add_u64 v[222:223], s[24:25], 0, v[136:137]
	global_load_lds_dwordx4 v[226:227], off
	v_lshl_add_u64 v[226:227], s[44:45], 0, v[134:135]
	s_add_i32 m0, s41, 0x2000
	s_nop 0
	global_load_lds_dwordx4 v[226:227], off
	v_lshl_add_u64 v[226:227], s[24:25], 0, v[138:139]
	s_mov_b32 m0, s34
	s_nop 0
	global_load_lds_dwordx4 v[226:227], off
	s_mov_b32 m0, s35
	s_nop 0
	global_load_lds_dwordx4 v[222:223], off
	s_waitcnt vmcnt(8)
	s_waitcnt lgkmcnt(0)
	s_barrier
	s_setprio 1
	s_waitcnt lgkmcnt(0)
	v_mfma_f32_16x16x32_bf16 v[66:69], v[148:151], v[200:203], v[66:69]
	v_mfma_f32_16x16x32_bf16 v[62:65], v[176:179], v[200:203], v[62:65]
	v_mfma_f32_16x16x32_bf16 v[50:53], v[148:151], v[208:211], v[50:53]
	v_mfma_f32_16x16x32_bf16 v[46:49], v[176:179], v[208:211], v[46:49]
	v_mfma_f32_16x16x32_bf16 v[34:37], v[148:151], v[216:219], v[34:37]
	v_mfma_f32_16x16x32_bf16 v[30:33], v[176:179], v[216:219], v[30:33]
	v_mfma_f32_16x16x32_bf16 v[18:21], v[148:151], v[240:243], v[18:21]
	v_mfma_f32_16x16x32_bf16 v[14:17], v[176:179], v[240:243], v[14:17]
	v_mfma_f32_16x16x32_bf16 v[66:69], v[172:175], v[204:207], v[66:69]
	v_mfma_f32_16x16x32_bf16 v[62:65], v[180:183], v[204:207], v[62:65]
	v_mfma_f32_16x16x32_bf16 v[50:53], v[172:175], v[212:215], v[50:53]
	v_mfma_f32_16x16x32_bf16 v[46:49], v[180:183], v[212:215], v[46:49]
	v_mfma_f32_16x16x32_bf16 v[34:37], v[172:175], v[236:239], v[34:37]
	v_mfma_f32_16x16x32_bf16 v[30:33], v[180:183], v[236:239], v[30:33]
	v_mfma_f32_16x16x32_bf16 v[18:21], v[172:175], v[244:247], v[18:21]
	v_mfma_f32_16x16x32_bf16 v[14:17], v[180:183], v[244:247], v[14:17]
	s_setprio 0
	s_setprio 1
	v_mfma_f32_16x16x32_bf16 v[58:61], v[184:187], v[200:203], v[58:61]
	v_mfma_f32_16x16x32_bf16 v[54:57], v[192:195], v[200:203], v[54:57]
	v_mfma_f32_16x16x32_bf16 v[42:45], v[184:187], v[208:211], v[42:45]
	v_mfma_f32_16x16x32_bf16 v[38:41], v[192:195], v[208:211], v[38:41]
	v_mfma_f32_16x16x32_bf16 v[26:29], v[184:187], v[216:219], v[26:29]
	v_mfma_f32_16x16x32_bf16 v[22:25], v[192:195], v[216:219], v[22:25]
	v_mfma_f32_16x16x32_bf16 v[10:13], v[184:187], v[240:243], v[10:13]
	v_mfma_f32_16x16x32_bf16 v[6:9], v[192:195], v[240:243], v[6:9]
	v_mfma_f32_16x16x32_bf16 v[58:61], v[188:191], v[204:207], v[58:61]
	v_mfma_f32_16x16x32_bf16 v[54:57], v[196:199], v[204:207], v[54:57]
	v_mfma_f32_16x16x32_bf16 v[42:45], v[188:191], v[212:215], v[42:45]
	v_mfma_f32_16x16x32_bf16 v[38:41], v[196:199], v[212:215], v[38:41]
	v_mfma_f32_16x16x32_bf16 v[26:29], v[188:191], v[236:239], v[26:29]
	v_mfma_f32_16x16x32_bf16 v[22:25], v[196:199], v[236:239], v[22:25]
	v_mfma_f32_16x16x32_bf16 v[10:13], v[188:191], v[244:247], v[10:13]
	v_mfma_f32_16x16x32_bf16 v[6:9], v[196:199], v[244:247], v[6:9]
	s_setprio 0
	s_barrier
.LpeelA_mid:
	s_add_i32 s41, 0, 0x18000
	v_add_u32_e32 v145, s41, v153
	s_add_i32 s44, 0, 0x1c000
	ds_read_b128 v[148:151], v145
	ds_read_b128 v[172:175], v145 offset:1024
	ds_read_b128 v[176:179], v145 offset:2048
	ds_read_b128 v[180:183], v145 offset:3072
	v_add_u32_e32 v145, s44, v153
	ds_read_b128 v[184:187], v145
	ds_read_b128 v[188:191], v145 offset:1024
	ds_read_b128 v[192:195], v145 offset:2048
	ds_read_b128 v[196:199], v145 offset:3072
	s_add_u32 s24, s24, 0x40000
	s_addc_u32 s25, s25, 0
	s_mov_b32 m0, s78
	v_lshl_add_u64 v[220:221], s[24:25], 0, v[138:139]
	ds_read_b128 v[200:203], v162 offset:32768
	ds_read_b128 v[204:207], v162 offset:33792
	ds_read_b128 v[208:211], v162 offset:34816
	ds_read_b128 v[212:215], v162 offset:35840
	ds_read_b128 v[216:219], v162 offset:36864
	ds_read_b128 v[236:239], v162 offset:37888
	ds_read_b128 v[240:243], v162 offset:38912
	ds_read_b128 v[244:247], v162 offset:39936
	global_load_lds_dwordx4 v[220:221], off
	v_lshl_add_u64 v[220:221], s[24:25], 0, v[136:137]
	s_mov_b32 m0, s79
	s_nop 0
	global_load_lds_dwordx4 v[220:221], off
	s_waitcnt vmcnt(8)
	s_waitcnt lgkmcnt(0)
	s_barrier
; #define PG8_STAGE(bufoff, gbase, voff) do { _Pragma("unroll") for (int _i = 0; _i < 2; ++_i) \
;         __builtin_amdgcn_global_load_lds((const unsigned*)((const char*)(gbase) + (voff)[_i]), (PG8_LAS unsigned*)(lds + (bufoff) + ldsw + _i * 8192), 16, 0, 0); } while (0)
; #define PG8_LDA(dst, b, h) do { _Pragma("unroll") for (int m = 0; m < 4; ++m) _Pragma("unroll") for (int k = 0; k < 2; ++k) dst[m][k] = *(const PG8_LAS bf16x8*)(lds + PG8_SA(b, h) + aoff + m * 2048 + k * 1024); } while (0)
; #define PG8_LDB(dst, b, h) do { _Pragma("unroll") for (int n = 0; n < 2; ++n) _Pragma("unroll") for (int k = 0; k < 2; ++k) dst[n][k] = *(const PG8_LAS bf16x8*)(lds + PG8_SB(b, h) + boff + n * 2048 + k * 1024); } while (0)
; #define PG8_MMA(ai, bj, At, Bt) do { __builtin_amdgcn_s_setprio(1); _Pragma("unroll") for (int m = 0; m < 4; ++m) _Pragma("unroll") for (int n = 0; n < 2; ++n) _Pragma("unroll") for (int k = 0; k < 2; ++k) \
;         acc[ai][bj][m][n] = __builtin_amdgcn_mfma_f32_16x16x32_bf16(Bt[n][k], At[m][k], acc[ai][bj][m][n], 0, 0, 0); __builtin_amdgcn_s_setprio(0); } while (0)
; #define PG8_WAIT_V(n) asm volatile("s_waitcnt vmcnt(" #n ")" ::: "memory")
; #define PG8_WAIT_L(n) asm volatile("s_waitcnt lgkmcnt(" #n ")" ::: "memory")
; #define PG8_BAR __builtin_amdgcn_s_barrier()
; #define PG8_SCHED __builtin_amdgcn_sched_barrier(0)
; template <class Epi, class Sched, bool ALIGN_EPI = false, bool SP2 = false>
; __device__ __forceinline__ void gemm_phase(PG8_LAS unsigned char* lds, const Gemm g, const Sched& S, const Epi& E) {
;     ...
;         for (int t = 0; t < nt; t += 2) {
;     ...
;             PG8_LDB(B0, 1, 0); PG8_LDB(B1, 1, 1); PG8_SCHED; PG8_LDA(At, 1, 0); PG8_STAGE(PG8_SA(0, 1), a2 + hstep, voffA);
;             PG8_WAIT_V(8); PG8_WAIT_L(0); PG8_BAR; PG8_MMA(0, 0, At, B0); PG8_MMA(0, 1, At, B1); PG8_BAR; PG8_SCHED;
;             PG8_LDA(At, 1, 1); PG8_STAGE(PG8_SB(1, 0), b3, voffB); PG8_STAGE(PG8_SB(1, 1), b3 + hstep, voffB); PG8_STAGE(PG8_SA(1, 0), a3, voffA);
;             PG8_WAIT_V(8); PG8_WAIT_L(0); PG8_BAR; PG8_MMA(1, 0, At, B0); PG8_MMA(1, 1, At, B1); PG8_BAR; PG8_SCHED;
	s_setprio 1
	s_waitcnt lgkmcnt(0)
	v_mfma_f32_16x16x32_bf16 v[130:133], v[148:151], v[200:203], v[130:133]
	v_mfma_f32_16x16x32_bf16 v[126:129], v[176:179], v[200:203], v[126:129]
	v_mfma_f32_16x16x32_bf16 v[114:117], v[148:151], v[208:211], v[114:117]
	v_mfma_f32_16x16x32_bf16 v[110:113], v[176:179], v[208:211], v[110:113]
	v_mfma_f32_16x16x32_bf16 v[98:101], v[148:151], v[216:219], v[98:101]
	v_mfma_f32_16x16x32_bf16 v[94:97], v[176:179], v[216:219], v[94:97]
	v_mfma_f32_16x16x32_bf16 v[82:85], v[148:151], v[240:243], v[82:85]
	v_mfma_f32_16x16x32_bf16 v[78:81], v[176:179], v[240:243], v[78:81]
	v_mfma_f32_16x16x32_bf16 v[130:133], v[172:175], v[204:207], v[130:133]
	v_mfma_f32_16x16x32_bf16 v[126:129], v[180:183], v[204:207], v[126:129]
	v_mfma_f32_16x16x32_bf16 v[114:117], v[172:175], v[212:215], v[114:117]
	v_mfma_f32_16x16x32_bf16 v[110:113], v[180:183], v[212:215], v[110:113]
	v_mfma_f32_16x16x32_bf16 v[98:101], v[172:175], v[236:239], v[98:101]
	v_mfma_f32_16x16x32_bf16 v[94:97], v[180:183], v[236:239], v[94:97]
	v_mfma_f32_16x16x32_bf16 v[82:85], v[172:175], v[244:247], v[82:85]
	v_mfma_f32_16x16x32_bf16 v[78:81], v[180:183], v[244:247], v[78:81]
	s_setprio 0
	s_setprio 1
	v_mfma_f32_16x16x32_bf16 v[122:125], v[184:187], v[200:203], v[122:125]
	v_mfma_f32_16x16x32_bf16 v[118:121], v[192:195], v[200:203], v[118:121]
	v_mfma_f32_16x16x32_bf16 v[106:109], v[184:187], v[208:211], v[106:109]
	v_mfma_f32_16x16x32_bf16 v[102:105], v[192:195], v[208:211], v[102:105]
	v_mfma_f32_16x16x32_bf16 v[90:93], v[184:187], v[216:219], v[90:93]
	v_mfma_f32_16x16x32_bf16 v[86:89], v[192:195], v[216:219], v[86:89]
	v_mfma_f32_16x16x32_bf16 v[74:77], v[184:187], v[240:243], v[74:77]
	v_mfma_f32_16x16x32_bf16 v[70:73], v[192:195], v[240:243], v[70:73]
	v_mfma_f32_16x16x32_bf16 v[122:125], v[188:191], v[204:207], v[122:125]
	v_mfma_f32_16x16x32_bf16 v[118:121], v[196:199], v[204:207], v[118:121]
	v_mfma_f32_16x16x32_bf16 v[106:109], v[188:191], v[212:215], v[106:109]
	v_mfma_f32_16x16x32_bf16 v[102:105], v[196:199], v[212:215], v[102:105]
	v_mfma_f32_16x16x32_bf16 v[90:93], v[188:191], v[236:239], v[90:93]
	v_mfma_f32_16x16x32_bf16 v[86:89], v[196:199], v[236:239], v[86:89]
	v_mfma_f32_16x16x32_bf16 v[74:77], v[188:191], v[244:247], v[74:77]
	v_mfma_f32_16x16x32_bf16 v[70:73], v[196:199], v[244:247], v[70:73]
	s_setprio 0
	s_barrier
	s_add_i32 s24, s41, s33
	v_lshl_add_u64 v[220:221], v[248:249], 0, s[68:69]
	s_mov_b32 m0, s24
	ds_read_b128 v[200:203], v162 offset:49152
	ds_read_b128 v[204:207], v162 offset:50176
	ds_read_b128 v[208:211], v162 offset:51200
	ds_read_b128 v[212:215], v162 offset:52224
	ds_read_b128 v[216:219], v162 offset:53248
	ds_read_b128 v[236:239], v162 offset:54272
	ds_read_b128 v[240:243], v162 offset:55296
	ds_read_b128 v[244:247], v162 offset:56320
	global_load_lds_dwordx4 v[220:221], off
	s_add_i32 m0, s24, 0x2000
	s_add_u32 s22, s22, 0x40080
	v_lshl_add_u64 v[220:221], v[250:251], 0, s[68:69]
	s_addc_u32 s23, s23, 0
	s_add_i32 s24, s44, s33
	global_load_lds_dwordx4 v[220:221], off
	v_lshl_add_u64 v[220:221], s[22:23], 0, v[156:157]
	s_mov_b32 m0, s24
	s_nop 0
	global_load_lds_dwordx4 v[220:221], off
	v_lshl_add_u64 v[220:221], s[22:23], 0, v[134:135]
	s_add_i32 m0, s24, 0x2000
	s_nop 0
	global_load_lds_dwordx4 v[220:221], off
	v_lshl_add_u64 v[220:221], v[226:227], 0, s[68:69]
	s_mov_b32 m0, s80
	s_nop 0
	global_load_lds_dwordx4 v[220:221], off
	v_lshl_add_u64 v[220:221], v[222:223], 0, s[68:69]
	s_mov_b32 m0, s81
	s_nop 0
	global_load_lds_dwordx4 v[220:221], off
	s_waitcnt vmcnt(8)
	s_waitcnt lgkmcnt(0)
	s_barrier
	s_setprio 1
	s_waitcnt lgkmcnt(0)
	v_mfma_f32_16x16x32_bf16 v[66:69], v[148:151], v[200:203], v[66:69]
	v_mfma_f32_16x16x32_bf16 v[62:65], v[176:179], v[200:203], v[62:65]
	v_mfma_f32_16x16x32_bf16 v[50:53], v[148:151], v[208:211], v[50:53]
	v_mfma_f32_16x16x32_bf16 v[46:49], v[176:179], v[208:211], v[46:49]
	v_mfma_f32_16x16x32_bf16 v[34:37], v[148:151], v[216:219], v[34:37]
	v_mfma_f32_16x16x32_bf16 v[30:33], v[176:179], v[216:219], v[30:33]
	v_mfma_f32_16x16x32_bf16 v[18:21], v[148:151], v[240:243], v[18:21]
	v_mfma_f32_16x16x32_bf16 v[14:17], v[176:179], v[240:243], v[14:17]
	v_mfma_f32_16x16x32_bf16 v[66:69], v[172:175], v[204:207], v[66:69]
	v_mfma_f32_16x16x32_bf16 v[62:65], v[180:183], v[204:207], v[62:65]
	v_mfma_f32_16x16x32_bf16 v[50:53], v[172:175], v[212:215], v[50:53]
	v_mfma_f32_16x16x32_bf16 v[46:49], v[180:183], v[212:215], v[46:49]
	v_mfma_f32_16x16x32_bf16 v[34:37], v[172:175], v[236:239], v[34:37]
	v_mfma_f32_16x16x32_bf16 v[30:33], v[180:183], v[236:239], v[30:33]
	v_mfma_f32_16x16x32_bf16 v[18:21], v[172:175], v[244:247], v[18:21]
	v_mfma_f32_16x16x32_bf16 v[14:17], v[180:183], v[244:247], v[14:17]
	s_setprio 0
	s_setprio 1
	v_mfma_f32_16x16x32_bf16 v[58:61], v[184:187], v[200:203], v[58:61]
	v_mfma_f32_16x16x32_bf16 v[54:57], v[192:195], v[200:203], v[54:57]
	v_mfma_f32_16x16x32_bf16 v[42:45], v[184:187], v[208:211], v[42:45]
	v_mfma_f32_16x16x32_bf16 v[38:41], v[192:195], v[208:211], v[38:41]
	v_mfma_f32_16x16x32_bf16 v[26:29], v[184:187], v[216:219], v[26:29]
	v_mfma_f32_16x16x32_bf16 v[22:25], v[192:195], v[216:219], v[22:25]
	v_mfma_f32_16x16x32_bf16 v[10:13], v[184:187], v[240:243], v[10:13]
	v_mfma_f32_16x16x32_bf16 v[6:9], v[192:195], v[240:243], v[6:9]
	v_mfma_f32_16x16x32_bf16 v[58:61], v[188:191], v[204:207], v[58:61]
	v_mfma_f32_16x16x32_bf16 v[54:57], v[196:199], v[204:207], v[54:57]
	v_mfma_f32_16x16x32_bf16 v[42:45], v[188:191], v[212:215], v[42:45]
	v_mfma_f32_16x16x32_bf16 v[38:41], v[196:199], v[212:215], v[38:41]
	v_mfma_f32_16x16x32_bf16 v[26:29], v[188:191], v[236:239], v[26:29]
	v_mfma_f32_16x16x32_bf16 v[22:25], v[196:199], v[236:239], v[22:25]
	v_mfma_f32_16x16x32_bf16 v[10:13], v[188:191], v[244:247], v[10:13]
	v_mfma_f32_16x16x32_bf16 v[6:9], v[196:199], v[244:247], v[6:9]
	s_setprio 0
	s_barrier
	s_add_i32 s40, s40, 2
	s_add_u32 s0, s0, 0x100
	s_addc_u32 s1, s1, 0
	s_add_u32 s38, s38, 0x100
	s_addc_u32 s39, s39, 0
	s_cmp_gt_u32 s40, 13
	s_cbranch_scc1 .LBB0_131

; #define PG8_STAGE(bufoff, gbase, voff) do { _Pragma("unroll") for (int _i = 0; _i < 2; ++_i) \
;         __builtin_amdgcn_global_load_lds((const unsigned*)((const char*)(gbase) + (voff)[_i]), (PG8_LAS unsigned*)(lds + (bufoff) + ldsw + _i * 8192), 16, 0, 0); } while (0)
; #define PG8_LDA(dst, b, h) do { _Pragma("unroll") for (int m = 0; m < 4; ++m) _Pragma("unroll") for (int k = 0; k < 2; ++k) dst[m][k] = *(const PG8_LAS bf16x8*)(lds + PG8_SA(b, h) + aoff + m * 2048 + k * 1024); } while (0)
; #define PG8_LDB(dst, b, h) do { _Pragma("unroll") for (int n = 0; n < 2; ++n) _Pragma("unroll") for (int k = 0; k < 2; ++k) dst[n][k] = *(const PG8_LAS bf16x8*)(lds + PG8_SB(b, h) + boff + n * 2048 + k * 1024); } while (0)
; #define PG8_WAIT_V(n) asm volatile("s_waitcnt vmcnt(" #n ")" ::: "memory")
; #define PG8_WAIT_L(n) asm volatile("s_waitcnt lgkmcnt(" #n ")" ::: "memory")
; #define PG8_BAR __builtin_amdgcn_s_barrier()
; template <class Epi, class Sched, bool ALIGN_EPI = false, bool SP2 = false>
; __device__ __forceinline__ void gemm_phase(PG8_LAS unsigned char* lds, const Gemm g, const Sched& S, const Epi& E) {
;     ...
;     for (;;) {
;         const bool has_next = S.next(ui + 1, nxt);
;         const char* nA = has_next ? (const char*)g.A + (size_t)nxt.pm * tstep : cA; const char* nB = has_next ? (const char*)g.Bt + (size_t)nxt.pn * tstep : cB;
;         for (int t = 0; t < nt; t += 2) {
;             const bool last = (t == nt - 2);
;             const char* a1 = cA + (size_t)(t + 1) * kstep;
;             const char* a2 = last ? nA : cA + (size_t)(t + 2) * kstep; const char* b2 = last ? nB : cB + (size_t)(t + 2) * kstep;
;             const char* a3 = a2 + kstep; const char* b3 = b2 + kstep;
;             if (last && has_next) S.a_ready(nxt);
;             if (last) E.pre(cur, wr, fr, rsv);
;             if constexpr (SP2) {
;             PG8_LDB(B0, 0, 0); PG8_LDB(B1, 0, 1); PG8_SCHED; PG8_LDA(At, 0, 0); PG8_STAGE(PG8_SA(1, 1), a1 + hstep, voffA);
;             PG8_WAIT_V(8); PG8_WAIT_L(0); PG8_BAR; PG8_MMA(0, 0, At, B0); PG8_MMA(0, 1, At, B1); PG8_BAR; PG8_SCHED;
;             PG8_LDA(At, 0, 1); PG8_STAGE(PG8_SB(0, 0), b2, voffB); PG8_STAGE(PG8_SB(0, 1), b2 + hstep, voffB); PG8_STAGE(PG8_SA(0, 0), a2, voffA);
;             PG8_WAIT_V(8); PG8_WAIT_L(0); PG8_BAR; PG8_MMA(1, 0, At, B0); PG8_MMA(1, 1, At, B1); PG8_BAR; PG8_SCHED;
.LBB0_954:
	s_ashr_i32 s25, s24, 31
	s_lshl_b64 s[38:39], s[24:25], 19
	s_add_u32 s96, s60, s38
	s_addc_u32 s97, s67, s39
	s_and_b64 s[38:39], s[8:9], exec
	s_cselect_b32 s25, s97, s11
	s_cselect_b32 s37, s96, s10
	s_ashr_i32 s23, s22, 31
	s_lshl_b64 s[38:39], s[22:23], 19
	s_add_u32 s78, s16, s38
	s_addc_u32 s79, s19, s39
	s_and_b64 s[38:39], s[8:9], exec
	s_cselect_b32 s23, s79, s5
	s_cselect_b32 s38, s78, s4
	s_add_u32 s10, s10, 0x40080
	s_addc_u32 s11, s11, 0
	s_add_u32 s39, s4, 0x100
	s_addc_u32 s40, s5, 0
	s_mov_b32 s41, -2
	s_waitcnt lgkmcnt(0)
	s_waitcnt vmcnt(0)
	s_branch .LBB0_955
.LpeelB:
	s_add_u32 s4, s10, 0xfffc0080
	s_addc_u32 s5, s11, -1
	s_add_i32 s44, 0, 0x10000
	s_cmp_eq_u32 s41, 12
	s_cselect_b32 vcc_hi, s25, s5
	s_cselect_b32 vcc_lo, s37, s4
	v_add_u32_e32 v152, s44, v172
	s_cselect_b32 s5, s23, s40
	s_cselect_b32 s4, s38, s39
	s_add_i32 s46, 0, 0x14000
	ds_read_b128 v[134:137], v152
	ds_read_b128 v[138:141], v152 offset:1024
	ds_read_b128 v[162:165], v152 offset:2048
	ds_read_b128 v[166:169], v152 offset:3072
	v_add_u32_e32 v152, s46, v172
	ds_read_b128 v[176:179], v152
	ds_read_b128 v[180:183], v152 offset:1024
	ds_read_b128 v[184:187], v152 offset:2048
	ds_read_b128 v[188:191], v152 offset:3072
	v_lshl_add_u64 v[152:153], s[10:11], 0, v[148:149]
	s_add_i32 m0, s80, 0xc000
	ds_read_b128 v[192:195], v174
	ds_read_b128 v[196:199], v174 offset:1024
	ds_read_b128 v[200:203], v174 offset:2048
	ds_read_b128 v[204:207], v174 offset:3072
	ds_read_b128 v[208:211], v174 offset:4096
	ds_read_b128 v[212:215], v174 offset:5120
	ds_read_b128 v[216:219], v174 offset:6144
	ds_read_b128 v[236:239], v174 offset:7168
	global_load_lds_dwordx4 v[152:153], off
	v_lshl_add_u64 v[152:153], s[10:11], 0, v[150:151]
	s_add_i32 m0, s80, 0xe000
	s_nop 0
	global_load_lds_dwordx4 v[152:153], off
	s_waitcnt vmcnt(8)
	s_waitcnt lgkmcnt(0)
	s_barrier
	s_setprio 1
	s_waitcnt lgkmcnt(0)
	v_mfma_f32_16x16x32_bf16 v[130:133], v[134:137], v[192:195], 0
	v_mfma_f32_16x16x32_bf16 v[126:129], v[162:165], v[192:195], 0
	v_mfma_f32_16x16x32_bf16 v[114:117], v[134:137], v[200:203], 0
	v_mfma_f32_16x16x32_bf16 v[110:113], v[162:165], v[200:203], 0
	v_mfma_f32_16x16x32_bf16 v[98:101], v[134:137], v[208:211], 0
	v_mfma_f32_16x16x32_bf16 v[94:97], v[162:165], v[208:211], 0
	v_mfma_f32_16x16x32_bf16 v[82:85], v[134:137], v[216:219], 0
	v_mfma_f32_16x16x32_bf16 v[78:81], v[162:165], v[216:219], 0
	v_mfma_f32_16x16x32_bf16 v[130:133], v[138:141], v[196:199], v[130:133]
	v_mfma_f32_16x16x32_bf16 v[126:129], v[166:169], v[196:199], v[126:129]
	v_mfma_f32_16x16x32_bf16 v[114:117], v[138:141], v[204:207], v[114:117]
	v_mfma_f32_16x16x32_bf16 v[110:113], v[166:169], v[204:207], v[110:113]
	v_mfma_f32_16x16x32_bf16 v[98:101], v[138:141], v[212:215], v[98:101]
	v_mfma_f32_16x16x32_bf16 v[94:97], v[166:169], v[212:215], v[94:97]
	v_mfma_f32_16x16x32_bf16 v[82:85], v[138:141], v[236:239], v[82:85]
	v_mfma_f32_16x16x32_bf16 v[78:81], v[166:169], v[236:239], v[78:81]
	s_setprio 0
	s_setprio 1
	v_mfma_f32_16x16x32_bf16 v[122:125], v[176:179], v[192:195], 0
	v_mfma_f32_16x16x32_bf16 v[118:121], v[184:187], v[192:195], 0
	v_mfma_f32_16x16x32_bf16 v[106:109], v[176:179], v[200:203], 0
	v_mfma_f32_16x16x32_bf16 v[102:105], v[184:187], v[200:203], 0
	v_mfma_f32_16x16x32_bf16 v[90:93], v[176:179], v[208:211], 0
	v_mfma_f32_16x16x32_bf16 v[86:89], v[184:187], v[208:211], 0
	v_mfma_f32_16x16x32_bf16 v[74:77], v[176:179], v[216:219], 0
	v_mfma_f32_16x16x32_bf16 v[70:73], v[184:187], v[216:219], 0
	v_mfma_f32_16x16x32_bf16 v[122:125], v[180:183], v[196:199], v[122:125]
	v_mfma_f32_16x16x32_bf16 v[118:121], v[188:191], v[196:199], v[118:121]
	v_mfma_f32_16x16x32_bf16 v[106:109], v[180:183], v[204:207], v[106:109]
	v_mfma_f32_16x16x32_bf16 v[102:105], v[188:191], v[204:207], v[102:105]
	v_mfma_f32_16x16x32_bf16 v[90:93], v[180:183], v[212:215], v[90:93]
	v_mfma_f32_16x16x32_bf16 v[86:89], v[188:191], v[212:215], v[86:89]
	v_mfma_f32_16x16x32_bf16 v[74:77], v[180:183], v[236:239], v[74:77]
	v_mfma_f32_16x16x32_bf16 v[70:73], v[188:191], v[236:239], v[70:73]
	s_setprio 0
	s_barrier
	s_add_i32 s44, s44, s33
	v_lshl_add_u64 v[152:153], s[4:5], 0, v[156:157]
	s_mov_b32 m0, s44
	ds_read_b128 v[192:195], v174 offset:16384
	ds_read_b128 v[196:199], v174 offset:17408
	ds_read_b128 v[200:203], v174 offset:18432
	ds_read_b128 v[204:207], v174 offset:19456
	ds_read_b128 v[208:211], v174 offset:20480
	ds_read_b128 v[212:215], v174 offset:21504
	ds_read_b128 v[216:219], v174 offset:22528
	ds_read_b128 v[236:239], v174 offset:23552
	global_load_lds_dwordx4 v[152:153], off
	s_add_i32 m0, s44, 0x2000
	s_add_u32 s44, s4, 0x40000
	v_lshl_add_u64 v[170:171], s[4:5], 0, v[142:143]
	s_addc_u32 s45, s5, 0
	s_add_i32 s46, s46, s33
	global_load_lds_dwordx4 v[170:171], off
	v_lshl_add_u64 v[220:221], s[44:45], 0, v[156:157]
	s_mov_b32 m0, s46
	v_lshl_add_u64 v[222:223], vcc, 0, v[144:145]
	global_load_lds_dwordx4 v[220:221], off
	v_lshl_add_u64 v[220:221], s[44:45], 0, v[142:143]
	s_add_i32 m0, s46, 0x2000
	s_nop 0
	global_load_lds_dwordx4 v[220:221], off
	v_lshl_add_u64 v[220:221], vcc, 0, v[146:147]
	s_mov_b32 m0, s80
	s_nop 0
	global_load_lds_dwordx4 v[220:221], off
	s_mov_b32 m0, s81
	s_nop 0
	global_load_lds_dwordx4 v[222:223], off
	s_waitcnt vmcnt(8)
	s_waitcnt lgkmcnt(0)
	s_barrier
; #define PG8_STAGE(bufoff, gbase, voff) do { _Pragma("unroll") for (int _i = 0; _i < 2; ++_i) \
;         __builtin_amdgcn_global_load_lds((const unsigned*)((const char*)(gbase) + (voff)[_i]), (PG8_LAS unsigned*)(lds + (bufoff) + ldsw + _i * 8192), 16, 0, 0); } while (0)
; #define PG8_LDA(dst, b, h) do { _Pragma("unroll") for (int m = 0; m < 4; ++m) _Pragma("unroll") for (int k = 0; k < 2; ++k) dst[m][k] = *(const PG8_LAS bf16x8*)(lds + PG8_SA(b, h) + aoff + m * 2048 + k * 1024); } while (0)
; #define PG8_LDB(dst, b, h) do { _Pragma("unroll") for (int n = 0; n < 2; ++n) _Pragma("unroll") for (int k = 0; k < 2; ++k) dst[n][k] = *(const PG8_LAS bf16x8*)(lds + PG8_SB(b, h) + boff + n * 2048 + k * 1024); } while (0)
; #define PG8_MMA(ai, bj, At, Bt) do { __builtin_amdgcn_s_setprio(1); _Pragma("unroll") for (int m = 0; m < 4; ++m) _Pragma("unroll") for (int n = 0; n < 2; ++n) _Pragma("unroll") for (int k = 0; k < 2; ++k) \
;         acc[ai][bj][m][n] = __builtin_amdgcn_mfma_f32_16x16x32_bf16(Bt[n][k], At[m][k], acc[ai][bj][m][n], 0, 0, 0); __builtin_amdgcn_s_setprio(0); } while (0)
; #define PG8_WAIT_V(n) asm volatile("s_waitcnt vmcnt(" #n ")" ::: "memory")
; #define PG8_WAIT_L(n) asm volatile("s_waitcnt lgkmcnt(" #n ")" ::: "memory")
; #define PG8_BAR __builtin_amdgcn_s_barrier()
; #define PG8_SCHED __builtin_amdgcn_sched_barrier(0)
; template <class Epi, class Sched, bool ALIGN_EPI = false, bool SP2 = false>
; __device__ __forceinline__ void gemm_phase(PG8_LAS unsigned char* lds, const Gemm g, const Sched& S, const Epi& E) {
;     ...
;             PG8_LDB(B0, 0, 0); PG8_LDB(B1, 0, 1); PG8_SCHED; PG8_LDA(At, 0, 0); PG8_STAGE(PG8_SA(1, 1), a1 + hstep, voffA);
;             PG8_WAIT_V(8); PG8_WAIT_L(0); PG8_BAR; PG8_MMA(0, 0, At, B0); PG8_MMA(0, 1, At, B1); PG8_BAR; PG8_SCHED;
;             PG8_LDA(At, 0, 1); PG8_STAGE(PG8_SB(0, 0), b2, voffB); PG8_STAGE(PG8_SB(0, 1), b2 + hstep, voffB); PG8_STAGE(PG8_SA(0, 0), a2, voffA);
;             PG8_WAIT_V(8); PG8_WAIT_L(0); PG8_BAR; PG8_MMA(1, 0, At, B0); PG8_MMA(1, 1, At, B1); PG8_BAR; PG8_SCHED;
	s_setprio 1
	s_waitcnt lgkmcnt(0)
	v_mfma_f32_16x16x32_bf16 v[66:69], v[134:137], v[192:195], 0
	v_mfma_f32_16x16x32_bf16 v[62:65], v[162:165], v[192:195], 0
	v_mfma_f32_16x16x32_bf16 v[50:53], v[134:137], v[200:203], 0
	v_mfma_f32_16x16x32_bf16 v[46:49], v[162:165], v[200:203], 0
	v_mfma_f32_16x16x32_bf16 v[34:37], v[134:137], v[208:211], 0
	v_mfma_f32_16x16x32_bf16 v[30:33], v[162:165], v[208:211], 0
	v_mfma_f32_16x16x32_bf16 v[18:21], v[134:137], v[216:219], 0
	v_mfma_f32_16x16x32_bf16 v[14:17], v[162:165], v[216:219], 0
	v_mfma_f32_16x16x32_bf16 v[66:69], v[138:141], v[196:199], v[66:69]
	v_mfma_f32_16x16x32_bf16 v[62:65], v[166:169], v[196:199], v[62:65]
	v_mfma_f32_16x16x32_bf16 v[50:53], v[138:141], v[204:207], v[50:53]
	v_mfma_f32_16x16x32_bf16 v[46:49], v[166:169], v[204:207], v[46:49]
	v_mfma_f32_16x16x32_bf16 v[34:37], v[138:141], v[212:215], v[34:37]
	v_mfma_f32_16x16x32_bf16 v[30:33], v[166:169], v[212:215], v[30:33]
	v_mfma_f32_16x16x32_bf16 v[18:21], v[138:141], v[236:239], v[18:21]
	v_mfma_f32_16x16x32_bf16 v[14:17], v[166:169], v[236:239], v[14:17]
	s_setprio 0
	s_setprio 1
	v_mfma_f32_16x16x32_bf16 v[58:61], v[176:179], v[192:195], 0
	v_mfma_f32_16x16x32_bf16 v[54:57], v[184:187], v[192:195], 0
	v_mfma_f32_16x16x32_bf16 v[42:45], v[176:179], v[200:203], 0
	v_mfma_f32_16x16x32_bf16 v[38:41], v[184:187], v[200:203], 0
	v_mfma_f32_16x16x32_bf16 v[26:29], v[176:179], v[208:211], 0
	v_mfma_f32_16x16x32_bf16 v[22:25], v[184:187], v[208:211], 0
	v_mfma_f32_16x16x32_bf16 v[10:13], v[176:179], v[216:219], 0
	v_mfma_f32_16x16x32_bf16 v[6:9], v[184:187], v[216:219], 0
	v_mfma_f32_16x16x32_bf16 v[58:61], v[180:183], v[196:199], v[58:61]
	v_mfma_f32_16x16x32_bf16 v[54:57], v[188:191], v[196:199], v[54:57]
	v_mfma_f32_16x16x32_bf16 v[42:45], v[180:183], v[204:207], v[42:45]
	v_mfma_f32_16x16x32_bf16 v[38:41], v[188:191], v[204:207], v[38:41]
	v_mfma_f32_16x16x32_bf16 v[26:29], v[180:183], v[212:215], v[26:29]
	v_mfma_f32_16x16x32_bf16 v[22:25], v[188:191], v[212:215], v[22:25]
	v_mfma_f32_16x16x32_bf16 v[10:13], v[180:183], v[236:239], v[10:13]
	v_mfma_f32_16x16x32_bf16 v[6:9], v[188:191], v[236:239], v[6:9]
	s_setprio 0
	s_barrier
	s_branch .LpeelB_mid
.LBB0_955:
	s_cmp_eq_u32 s41, -2
	s_cbranch_scc1 .LpeelB
	s_add_u32 s4, s10, 0xfffc0080
	s_addc_u32 s5, s11, -1
	s_add_i32 s44, 0, 0x10000
	s_cmp_eq_u32 s41, 12
	s_cselect_b32 vcc_hi, s25, s5
	s_cselect_b32 vcc_lo, s37, s4
	v_add_u32_e32 v152, s44, v172
	s_cselect_b32 s5, s23, s40
	s_cselect_b32 s4, s38, s39
	s_add_i32 s46, 0, 0x14000
	ds_read_b128 v[134:137], v152
	ds_read_b128 v[138:141], v152 offset:1024
	ds_read_b128 v[162:165], v152 offset:2048
	ds_read_b128 v[166:169], v152 offset:3072
	v_add_u32_e32 v152, s46, v172
	ds_read_b128 v[176:179], v152
	ds_read_b128 v[180:183], v152 offset:1024
	ds_read_b128 v[184:187], v152 offset:2048
	ds_read_b128 v[188:191], v152 offset:3072
	v_lshl_add_u64 v[152:153], s[10:11], 0, v[148:149]
	s_add_i32 m0, s80, 0xc000
	ds_read_b128 v[192:195], v174
	ds_read_b128 v[196:199], v174 offset:1024
	ds_read_b128 v[200:203], v174 offset:2048
	ds_read_b128 v[204:207], v174 offset:3072
	ds_read_b128 v[208:211], v174 offset:4096
	ds_read_b128 v[212:215], v174 offset:5120
	ds_read_b128 v[216:219], v174 offset:6144
	ds_read_b128 v[236:239], v174 offset:7168
	global_load_lds_dwordx4 v[152:153], off
	v_lshl_add_u64 v[152:153], s[10:11], 0, v[150:151]
	s_add_i32 m0, s80, 0xe000
	s_nop 0
	global_load_lds_dwordx4 v[152:153], off
	s_waitcnt vmcnt(8)
	s_waitcnt lgkmcnt(0)
	s_barrier
	s_setprio 1
	s_waitcnt lgkmcnt(0)
	v_mfma_f32_16x16x32_bf16 v[130:133], v[134:137], v[192:195], v[130:133]
	v_mfma_f32_16x16x32_bf16 v[126:129], v[162:165], v[192:195], v[126:129]
	v_mfma_f32_16x16x32_bf16 v[114:117], v[134:137], v[200:203], v[114:117]
	v_mfma_f32_16x16x32_bf16 v[110:113], v[162:165], v[200:203], v[110:113]
	v_mfma_f32_16x16x32_bf16 v[98:101], v[134:137], v[208:211], v[98:101]
	v_mfma_f32_16x16x32_bf16 v[94:97], v[162:165], v[208:211], v[94:97]
	v_mfma_f32_16x16x32_bf16 v[82:85], v[134:137], v[216:219], v[82:85]
	v_mfma_f32_16x16x32_bf16 v[78:81], v[162:165], v[216:219], v[78:81]
	v_mfma_f32_16x16x32_bf16 v[130:133], v[138:141], v[196:199], v[130:133]
	v_mfma_f32_16x16x32_bf16 v[126:129], v[166:169], v[196:199], v[126:129]
	v_mfma_f32_16x16x32_bf16 v[114:117], v[138:141], v[204:207], v[114:117]
	v_mfma_f32_16x16x32_bf16 v[110:113], v[166:169], v[204:207], v[110:113]
	v_mfma_f32_16x16x32_bf16 v[98:101], v[138:141], v[212:215], v[98:101]
	v_mfma_f32_16x16x32_bf16 v[94:97], v[166:169], v[212:215], v[94:97]
	v_mfma_f32_16x16x32_bf16 v[82:85], v[138:141], v[236:239], v[82:85]
	v_mfma_f32_16x16x32_bf16 v[78:81], v[166:169], v[236:239], v[78:81]
	s_setprio 0
	s_setprio 1
	v_mfma_f32_16x16x32_bf16 v[122:125], v[176:179], v[192:195], v[122:125]
	v_mfma_f32_16x16x32_bf16 v[118:121], v[184:187], v[192:195], v[118:121]
	v_mfma_f32_16x16x32_bf16 v[106:109], v[176:179], v[200:203], v[106:109]
	v_mfma_f32_16x16x32_bf16 v[102:105], v[184:187], v[200:203], v[102:105]
	v_mfma_f32_16x16x32_bf16 v[90:93], v[176:179], v[208:211], v[90:93]
	v_mfma_f32_16x16x32_bf16 v[86:89], v[184:187], v[208:211], v[86:89]
	v_mfma_f32_16x16x32_bf16 v[74:77], v[176:179], v[216:219], v[74:77]
	v_mfma_f32_16x16x32_bf16 v[70:73], v[184:187], v[216:219], v[70:73]
	v_mfma_f32_16x16x32_bf16 v[122:125], v[180:183], v[196:199], v[122:125]
	v_mfma_f32_16x16x32_bf16 v[118:121], v[188:191], v[196:199], v[118:121]
	v_mfma_f32_16x16x32_bf16 v[106:109], v[180:183], v[204:207], v[106:109]
	v_mfma_f32_16x16x32_bf16 v[102:105], v[188:191], v[204:207], v[102:105]
	v_mfma_f32_16x16x32_bf16 v[90:93], v[180:183], v[212:215], v[90:93]
	v_mfma_f32_16x16x32_bf16 v[86:89], v[188:191], v[212:215], v[86:89]
	v_mfma_f32_16x16x32_bf16 v[74:77], v[180:183], v[236:239], v[74:77]
	v_mfma_f32_16x16x32_bf16 v[70:73], v[188:191], v[236:239], v[70:73]
	s_setprio 0
	s_barrier
; #define PG8_STAGE(bufoff, gbase, voff) do { _Pragma("unroll") for (int _i = 0; _i < 2; ++_i) \
;         __builtin_amdgcn_global_load_lds((const unsigned*)((const char*)(gbase) + (voff)[_i]), (PG8_LAS unsigned*)(lds + (bufoff) + ldsw + _i * 8192), 16, 0, 0); } while (0)
; #define PG8_LDA(dst, b, h) do { _Pragma("unroll") for (int m = 0; m < 4; ++m) _Pragma("unroll") for (int k = 0; k < 2; ++k) dst[m][k] = *(const PG8_LAS bf16x8*)(lds + PG8_SA(b, h) + aoff + m * 2048 + k * 1024); } while (0)
; #define PG8_LDB(dst, b, h) do { _Pragma("unroll") for (int n = 0; n < 2; ++n) _Pragma("unroll") for (int k = 0; k < 2; ++k) dst[n][k] = *(const PG8_LAS bf16x8*)(lds + PG8_SB(b, h) + boff + n * 2048 + k * 1024); } while (0)
; #define PG8_MMA(ai, bj, At, Bt) do { __builtin_amdgcn_s_setprio(1); _Pragma("unroll") for (int m = 0; m < 4; ++m) _Pragma("unroll") for (int n = 0; n < 2; ++n) _Pragma("unroll") for (int k = 0; k < 2; ++k) \
;         acc[ai][bj][m][n] = __builtin_amdgcn_mfma_f32_16x16x32_bf16(Bt[n][k], At[m][k], acc[ai][bj][m][n], 0, 0, 0); __builtin_amdgcn_s_setprio(0); } while (0)
; #define PG8_WAIT_V(n) asm volatile("s_waitcnt vmcnt(" #n ")" ::: "memory")
; #define PG8_WAIT_L(n) asm volatile("s_waitcnt lgkmcnt(" #n ")" ::: "memory")
; #define PG8_BAR __builtin_amdgcn_s_barrier()
; #define PG8_SCHED __builtin_amdgcn_sched_barrier(0)
; template <class Epi, class Sched, bool ALIGN_EPI = false, bool SP2 = false>
; __device__ __forceinline__ void gemm_phase(PG8_LAS unsigned char* lds, const Gemm g, const Sched& S, const Epi& E) {
;     ...
;             PG8_LDA(At, 0, 1); PG8_STAGE(PG8_SB(0, 0), b2, voffB); PG8_STAGE(PG8_SB(0, 1), b2 + hstep, voffB); PG8_STAGE(PG8_SA(0, 0), a2, voffA);
;             PG8_WAIT_V(8); PG8_WAIT_L(0); PG8_BAR; PG8_MMA(1, 0, At, B0); PG8_MMA(1, 1, At, B1); PG8_BAR; PG8_SCHED;
;             PG8_LDB(B0, 1, 0); PG8_LDB(B1, 1, 1); PG8_SCHED; PG8_LDA(At, 1, 0); PG8_STAGE(PG8_SA(0, 1), a2 + hstep, voffA);
;             PG8_WAIT_V(8); PG8_WAIT_L(0); PG8_BAR; PG8_MMA(0, 0, At, B0); PG8_MMA(0, 1, At, B1); PG8_BAR; PG8_SCHED;
	s_add_i32 s44, s44, s33
	v_lshl_add_u64 v[152:153], s[4:5], 0, v[156:157]
	s_mov_b32 m0, s44
	ds_read_b128 v[192:195], v174 offset:16384
	ds_read_b128 v[196:199], v174 offset:17408
	ds_read_b128 v[200:203], v174 offset:18432
	ds_read_b128 v[204:207], v174 offset:19456
	ds_read_b128 v[208:211], v174 offset:20480
	ds_read_b128 v[212:215], v174 offset:21504
	ds_read_b128 v[216:219], v174 offset:22528
	ds_read_b128 v[236:239], v174 offset:23552
	global_load_lds_dwordx4 v[152:153], off
	s_add_i32 m0, s44, 0x2000
	s_add_u32 s44, s4, 0x40000
	v_lshl_add_u64 v[170:171], s[4:5], 0, v[142:143]
	s_addc_u32 s45, s5, 0
	s_add_i32 s46, s46, s33
	global_load_lds_dwordx4 v[170:171], off
	v_lshl_add_u64 v[220:221], s[44:45], 0, v[156:157]
	s_mov_b32 m0, s46
	v_lshl_add_u64 v[222:223], vcc, 0, v[144:145]
	global_load_lds_dwordx4 v[220:221], off
	v_lshl_add_u64 v[220:221], s[44:45], 0, v[142:143]
	s_add_i32 m0, s46, 0x2000
	s_nop 0
	global_load_lds_dwordx4 v[220:221], off
	v_lshl_add_u64 v[220:221], vcc, 0, v[146:147]
	s_mov_b32 m0, s80
	s_nop 0
	global_load_lds_dwordx4 v[220:221], off
	s_mov_b32 m0, s81
	s_nop 0
	global_load_lds_dwordx4 v[222:223], off
	s_waitcnt vmcnt(8)
	s_waitcnt lgkmcnt(0)
	s_barrier
	s_setprio 1
	s_waitcnt lgkmcnt(0)
	v_mfma_f32_16x16x32_bf16 v[66:69], v[134:137], v[192:195], v[66:69]
	v_mfma_f32_16x16x32_bf16 v[62:65], v[162:165], v[192:195], v[62:65]
	v_mfma_f32_16x16x32_bf16 v[50:53], v[134:137], v[200:203], v[50:53]
	v_mfma_f32_16x16x32_bf16 v[46:49], v[162:165], v[200:203], v[46:49]
	v_mfma_f32_16x16x32_bf16 v[34:37], v[134:137], v[208:211], v[34:37]
	v_mfma_f32_16x16x32_bf16 v[30:33], v[162:165], v[208:211], v[30:33]
	v_mfma_f32_16x16x32_bf16 v[18:21], v[134:137], v[216:219], v[18:21]
	v_mfma_f32_16x16x32_bf16 v[14:17], v[162:165], v[216:219], v[14:17]
	v_mfma_f32_16x16x32_bf16 v[66:69], v[138:141], v[196:199], v[66:69]
	v_mfma_f32_16x16x32_bf16 v[62:65], v[166:169], v[196:199], v[62:65]
	v_mfma_f32_16x16x32_bf16 v[50:53], v[138:141], v[204:207], v[50:53]
	v_mfma_f32_16x16x32_bf16 v[46:49], v[166:169], v[204:207], v[46:49]
	v_mfma_f32_16x16x32_bf16 v[34:37], v[138:141], v[212:215], v[34:37]
	v_mfma_f32_16x16x32_bf16 v[30:33], v[166:169], v[212:215], v[30:33]
	v_mfma_f32_16x16x32_bf16 v[18:21], v[138:141], v[236:239], v[18:21]
	v_mfma_f32_16x16x32_bf16 v[14:17], v[166:169], v[236:239], v[14:17]
	s_setprio 0
	s_setprio 1
	v_mfma_f32_16x16x32_bf16 v[58:61], v[176:179], v[192:195], v[58:61]
	v_mfma_f32_16x16x32_bf16 v[54:57], v[184:187], v[192:195], v[54:57]
	v_mfma_f32_16x16x32_bf16 v[42:45], v[176:179], v[200:203], v[42:45]
	v_mfma_f32_16x16x32_bf16 v[38:41], v[184:187], v[200:203], v[38:41]
	v_mfma_f32_16x16x32_bf16 v[26:29], v[176:179], v[208:211], v[26:29]
	v_mfma_f32_16x16x32_bf16 v[22:25], v[184:187], v[208:211], v[22:25]
	v_mfma_f32_16x16x32_bf16 v[10:13], v[176:179], v[216:219], v[10:13]
	v_mfma_f32_16x16x32_bf16 v[6:9], v[184:187], v[216:219], v[6:9]
	v_mfma_f32_16x16x32_bf16 v[58:61], v[180:183], v[196:199], v[58:61]
	v_mfma_f32_16x16x32_bf16 v[54:57], v[188:191], v[196:199], v[54:57]
	v_mfma_f32_16x16x32_bf16 v[42:45], v[180:183], v[204:207], v[42:45]
	v_mfma_f32_16x16x32_bf16 v[38:41], v[188:191], v[204:207], v[38:41]
	v_mfma_f32_16x16x32_bf16 v[26:29], v[180:183], v[212:215], v[26:29]
	v_mfma_f32_16x16x32_bf16 v[22:25], v[188:191], v[212:215], v[22:25]
	v_mfma_f32_16x16x32_bf16 v[10:13], v[180:183], v[236:239], v[10:13]
	v_mfma_f32_16x16x32_bf16 v[6:9], v[188:191], v[236:239], v[6:9]
	s_setprio 0
	s_barrier
.LpeelB_mid:
	s_add_i32 s46, 0, 0x18000
	s_add_i32 s47, 0, 0x1c000
	v_add_u32_e32 v166, s46, v172
	v_add_u32_e32 v175, s47, v172
	ds_read_b128 v[134:137], v166
	ds_read_b128 v[138:141], v166 offset:1024
	ds_read_b128 v[162:165], v166 offset:2048
	ds_read_b128 v[166:169], v166 offset:3072
	ds_read_b128 v[176:179], v175
	ds_read_b128 v[180:183], v175 offset:1024
	ds_read_b128 v[184:187], v175 offset:2048
	ds_read_b128 v[188:191], v175 offset:3072
	s_add_u32 s44, vcc_lo, 0x40000
	s_addc_u32 s45, vcc_hi, 0
	s_mov_b32 m0, s87
	v_lshl_add_u64 v[226:227], s[44:45], 0, v[146:147]
	ds_read_b128 v[192:195], v174 offset:32768
	ds_read_b128 v[196:199], v174 offset:33792
	ds_read_b128 v[200:203], v174 offset:34816
	ds_read_b128 v[204:207], v174 offset:35840
	ds_read_b128 v[208:211], v174 offset:36864
	ds_read_b128 v[212:215], v174 offset:37888
	ds_read_b128 v[216:219], v174 offset:38912
	ds_read_b128 v[236:239], v174 offset:39936
	global_load_lds_dwordx4 v[226:227], off
	v_lshl_add_u64 v[226:227], s[44:45], 0, v[144:145]
	s_mov_b32 m0, s88
	s_nop 0
	global_load_lds_dwordx4 v[226:227], off
	s_waitcnt vmcnt(8)
	s_waitcnt lgkmcnt(0)
	s_barrier
; #define PG8_STAGE(bufoff, gbase, voff) do { _Pragma("unroll") for (int _i = 0; _i < 2; ++_i) \
;         __builtin_amdgcn_global_load_lds((const unsigned*)((const char*)(gbase) + (voff)[_i]), (PG8_LAS unsigned*)(lds + (bufoff) + ldsw + _i * 8192), 16, 0, 0); } while (0)
; #define PG8_LDA(dst, b, h) do { _Pragma("unroll") for (int m = 0; m < 4; ++m) _Pragma("unroll") for (int k = 0; k < 2; ++k) dst[m][k] = *(const PG8_LAS bf16x8*)(lds + PG8_SA(b, h) + aoff + m * 2048 + k * 1024); } while (0)
; #define PG8_LDB(dst, b, h) do { _Pragma("unroll") for (int n = 0; n < 2; ++n) _Pragma("unroll") for (int k = 0; k < 2; ++k) dst[n][k] = *(const PG8_LAS bf16x8*)(lds + PG8_SB(b, h) + boff + n * 2048 + k * 1024); } while (0)
; #define PG8_MMA(ai, bj, At, Bt) do { __builtin_amdgcn_s_setprio(1); _Pragma("unroll") for (int m = 0; m < 4; ++m) _Pragma("unroll") for (int n = 0; n < 2; ++n) _Pragma("unroll") for (int k = 0; k < 2; ++k) \
;         acc[ai][bj][m][n] = __builtin_amdgcn_mfma_f32_16x16x32_bf16(Bt[n][k], At[m][k], acc[ai][bj][m][n], 0, 0, 0); __builtin_amdgcn_s_setprio(0); } while (0)
; #define PG8_WAIT_V(n) asm volatile("s_waitcnt vmcnt(" #n ")" ::: "memory")
; #define PG8_WAIT_L(n) asm volatile("s_waitcnt lgkmcnt(" #n ")" ::: "memory")
; #define PG8_BAR __builtin_amdgcn_s_barrier()
; #define PG8_SCHED __builtin_amdgcn_sched_barrier(0)
; template <class Epi, class Sched, bool ALIGN_EPI = false, bool SP2 = false>
; __device__ __forceinline__ void gemm_phase(PG8_LAS unsigned char* lds, const Gemm g, const Sched& S, const Epi& E) {
;     ...
;             PG8_LDB(B0, 1, 0); PG8_LDB(B1, 1, 1); PG8_SCHED; PG8_LDA(At, 1, 0); PG8_STAGE(PG8_SA(0, 1), a2 + hstep, voffA);
;             PG8_WAIT_V(8); PG8_WAIT_L(0); PG8_BAR; PG8_MMA(0, 0, At, B0); PG8_MMA(0, 1, At, B1); PG8_BAR; PG8_SCHED;
;             PG8_LDA(At, 1, 1); PG8_STAGE(PG8_SB(1, 0), b3, voffB); PG8_STAGE(PG8_SB(1, 1), b3 + hstep, voffB); PG8_STAGE(PG8_SA(1, 0), a3, voffA);
;             PG8_WAIT_V(8); PG8_WAIT_L(0); PG8_BAR; PG8_MMA(1, 0, At, B0); PG8_MMA(1, 1, At, B1); PG8_BAR; PG8_SCHED;
	s_setprio 1
	s_waitcnt lgkmcnt(0)
	v_mfma_f32_16x16x32_bf16 v[130:133], v[134:137], v[192:195], v[130:133]
	v_mfma_f32_16x16x32_bf16 v[126:129], v[162:165], v[192:195], v[126:129]
	v_mfma_f32_16x16x32_bf16 v[114:117], v[134:137], v[200:203], v[114:117]
	v_mfma_f32_16x16x32_bf16 v[110:113], v[162:165], v[200:203], v[110:113]
	v_mfma_f32_16x16x32_bf16 v[98:101], v[134:137], v[208:211], v[98:101]
	v_mfma_f32_16x16x32_bf16 v[94:97], v[162:165], v[208:211], v[94:97]
	v_mfma_f32_16x16x32_bf16 v[82:85], v[134:137], v[216:219], v[82:85]
	v_mfma_f32_16x16x32_bf16 v[78:81], v[162:165], v[216:219], v[78:81]
	v_mfma_f32_16x16x32_bf16 v[130:133], v[138:141], v[196:199], v[130:133]
	v_mfma_f32_16x16x32_bf16 v[126:129], v[166:169], v[196:199], v[126:129]
	v_mfma_f32_16x16x32_bf16 v[114:117], v[138:141], v[204:207], v[114:117]
	v_mfma_f32_16x16x32_bf16 v[110:113], v[166:169], v[204:207], v[110:113]
	v_mfma_f32_16x16x32_bf16 v[98:101], v[138:141], v[212:215], v[98:101]
	v_mfma_f32_16x16x32_bf16 v[94:97], v[166:169], v[212:215], v[94:97]
	v_mfma_f32_16x16x32_bf16 v[82:85], v[138:141], v[236:239], v[82:85]
	v_mfma_f32_16x16x32_bf16 v[78:81], v[166:169], v[236:239], v[78:81]
	s_setprio 0
	s_setprio 1
	v_mfma_f32_16x16x32_bf16 v[122:125], v[176:179], v[192:195], v[122:125]
	v_mfma_f32_16x16x32_bf16 v[118:121], v[184:187], v[192:195], v[118:121]
	v_mfma_f32_16x16x32_bf16 v[106:109], v[176:179], v[200:203], v[106:109]
	v_mfma_f32_16x16x32_bf16 v[102:105], v[184:187], v[200:203], v[102:105]
	v_mfma_f32_16x16x32_bf16 v[90:93], v[176:179], v[208:211], v[90:93]
	v_mfma_f32_16x16x32_bf16 v[86:89], v[184:187], v[208:211], v[86:89]
	v_mfma_f32_16x16x32_bf16 v[74:77], v[176:179], v[216:219], v[74:77]
	v_mfma_f32_16x16x32_bf16 v[70:73], v[184:187], v[216:219], v[70:73]
	v_mfma_f32_16x16x32_bf16 v[122:125], v[180:183], v[196:199], v[122:125]
	v_mfma_f32_16x16x32_bf16 v[118:121], v[188:191], v[196:199], v[118:121]
	v_mfma_f32_16x16x32_bf16 v[106:109], v[180:183], v[204:207], v[106:109]
	v_mfma_f32_16x16x32_bf16 v[102:105], v[188:191], v[204:207], v[102:105]
	v_mfma_f32_16x16x32_bf16 v[90:93], v[180:183], v[212:215], v[90:93]
	v_mfma_f32_16x16x32_bf16 v[86:89], v[188:191], v[212:215], v[86:89]
	v_mfma_f32_16x16x32_bf16 v[74:77], v[180:183], v[236:239], v[74:77]
	v_mfma_f32_16x16x32_bf16 v[70:73], v[188:191], v[236:239], v[70:73]
	s_setprio 0
	s_barrier
	s_add_i32 s44, s46, s33
	v_lshl_add_u64 v[152:153], v[152:153], 0, s[68:69]
	s_mov_b32 m0, s44
	ds_read_b128 v[192:195], v174 offset:49152
	ds_read_b128 v[196:199], v174 offset:50176
	ds_read_b128 v[200:203], v174 offset:51200
	ds_read_b128 v[204:207], v174 offset:52224
	ds_read_b128 v[208:211], v174 offset:53248
	ds_read_b128 v[212:215], v174 offset:54272
	ds_read_b128 v[216:219], v174 offset:55296
	ds_read_b128 v[236:239], v174 offset:56320
	global_load_lds_dwordx4 v[152:153], off
	s_add_i32 m0, s44, 0x2000
	s_add_u32 s4, s4, 0x40080
	v_lshl_add_u64 v[152:153], v[170:171], 0, s[68:69]
	s_addc_u32 s5, s5, 0
	s_add_i32 s44, s47, s33
	global_load_lds_dwordx4 v[152:153], off
	v_lshl_add_u64 v[152:153], s[4:5], 0, v[156:157]
	s_mov_b32 m0, s44
	s_nop 0
	global_load_lds_dwordx4 v[152:153], off
	v_lshl_add_u64 v[152:153], s[4:5], 0, v[142:143]
	s_add_i32 m0, s44, 0x2000
	s_nop 0
	global_load_lds_dwordx4 v[152:153], off
	v_lshl_add_u64 v[152:153], v[220:221], 0, s[68:69]
	s_mov_b32 m0, s89
	s_nop 0
	global_load_lds_dwordx4 v[152:153], off
	v_lshl_add_u64 v[152:153], v[222:223], 0, s[68:69]
	s_mov_b32 m0, s90
	s_nop 0
	global_load_lds_dwordx4 v[152:153], off
	s_waitcnt vmcnt(8)
	s_waitcnt lgkmcnt(0)
	s_barrier
	s_setprio 1
	s_waitcnt lgkmcnt(0)
	v_mfma_f32_16x16x32_bf16 v[66:69], v[134:137], v[192:195], v[66:69]
	v_mfma_f32_16x16x32_bf16 v[62:65], v[162:165], v[192:195], v[62:65]
	v_mfma_f32_16x16x32_bf16 v[50:53], v[134:137], v[200:203], v[50:53]
	v_mfma_f32_16x16x32_bf16 v[46:49], v[162:165], v[200:203], v[46:49]
	v_mfma_f32_16x16x32_bf16 v[34:37], v[134:137], v[208:211], v[34:37]
	v_mfma_f32_16x16x32_bf16 v[30:33], v[162:165], v[208:211], v[30:33]
	v_mfma_f32_16x16x32_bf16 v[18:21], v[134:137], v[216:219], v[18:21]
	v_mfma_f32_16x16x32_bf16 v[14:17], v[162:165], v[216:219], v[14:17]
	v_mfma_f32_16x16x32_bf16 v[66:69], v[138:141], v[196:199], v[66:69]
	v_mfma_f32_16x16x32_bf16 v[62:65], v[166:169], v[196:199], v[62:65]
	v_mfma_f32_16x16x32_bf16 v[50:53], v[138:141], v[204:207], v[50:53]
	v_mfma_f32_16x16x32_bf16 v[46:49], v[166:169], v[204:207], v[46:49]
	v_mfma_f32_16x16x32_bf16 v[34:37], v[138:141], v[212:215], v[34:37]
	v_mfma_f32_16x16x32_bf16 v[30:33], v[166:169], v[212:215], v[30:33]
	v_mfma_f32_16x16x32_bf16 v[18:21], v[138:141], v[236:239], v[18:21]
	v_mfma_f32_16x16x32_bf16 v[14:17], v[166:169], v[236:239], v[14:17]
	s_setprio 0
	s_setprio 1
	v_mfma_f32_16x16x32_bf16 v[58:61], v[176:179], v[192:195], v[58:61]
	v_mfma_f32_16x16x32_bf16 v[54:57], v[184:187], v[192:195], v[54:57]
	v_mfma_f32_16x16x32_bf16 v[42:45], v[176:179], v[200:203], v[42:45]
	v_mfma_f32_16x16x32_bf16 v[38:41], v[184:187], v[200:203], v[38:41]
	v_mfma_f32_16x16x32_bf16 v[26:29], v[176:179], v[208:211], v[26:29]
	v_mfma_f32_16x16x32_bf16 v[22:25], v[184:187], v[208:211], v[22:25]
	v_mfma_f32_16x16x32_bf16 v[10:13], v[176:179], v[216:219], v[10:13]
	v_mfma_f32_16x16x32_bf16 v[6:9], v[184:187], v[216:219], v[6:9]
	v_mfma_f32_16x16x32_bf16 v[58:61], v[180:183], v[196:199], v[58:61]
	v_mfma_f32_16x16x32_bf16 v[54:57], v[188:191], v[196:199], v[54:57]
	v_mfma_f32_16x16x32_bf16 v[42:45], v[180:183], v[204:207], v[42:45]
	v_mfma_f32_16x16x32_bf16 v[38:41], v[188:191], v[204:207], v[38:41]
	v_mfma_f32_16x16x32_bf16 v[26:29], v[180:183], v[212:215], v[26:29]
	v_mfma_f32_16x16x32_bf16 v[22:25], v[188:191], v[212:215], v[22:25]
	v_mfma_f32_16x16x32_bf16 v[10:13], v[180:183], v[236:239], v[10:13]
	v_mfma_f32_16x16x32_bf16 v[6:9], v[188:191], v[236:239], v[6:9]
	s_setprio 0
	s_barrier
	s_add_i32 s41, s41, 2
	s_add_u32 s10, s10, 0x100
	s_addc_u32 s11, s11, 0
	s_add_u32 s39, s39, 0x100
	s_addc_u32 s40, s40, 0
	s_cmp_gt_u32 s41, 13
	s_cbranch_scc0 .LBB0_955
	s_and_b64 vcc, exec, s[14:15]
	s_cbranch_vccz .LBB0_958
	s_barrier

; #define PG8_STAGE(bufoff, gbase, voff) do { _Pragma("unroll") for (int _i = 0; _i < 2; ++_i) \
;         __builtin_amdgcn_global_load_lds((const unsigned*)((const char*)(gbase) + (voff)[_i]), (PG8_LAS unsigned*)(lds + (bufoff) + ldsw + _i * 8192), 16, 0, 0); } while (0)
; #define PG8_LDA(dst, b, h) do { _Pragma("unroll") for (int m = 0; m < 4; ++m) _Pragma("unroll") for (int k = 0; k < 2; ++k) dst[m][k] = *(const PG8_LAS bf16x8*)(lds + PG8_SA(b, h) + aoff + m * 2048 + k * 1024); } while (0)
; #define PG8_LDB(dst, b, h) do { _Pragma("unroll") for (int n = 0; n < 2; ++n) _Pragma("unroll") for (int k = 0; k < 2; ++k) dst[n][k] = *(const PG8_LAS bf16x8*)(lds + PG8_SB(b, h) + boff + n * 2048 + k * 1024); } while (0)
; #define PG8_MMA(ai, bj, At, Bt) do { __builtin_amdgcn_s_setprio(1); _Pragma("unroll") for (int m = 0; m < 4; ++m) _Pragma("unroll") for (int n = 0; n < 2; ++n) _Pragma("unroll") for (int k = 0; k < 2; ++k) \
;         acc[ai][bj][m][n] = __builtin_amdgcn_mfma_f32_16x16x32_bf16(Bt[n][k], At[m][k], acc[ai][bj][m][n], 0, 0, 0); __builtin_amdgcn_s_setprio(0); } while (0)
; #define PG8_WAIT_V(n) asm volatile("s_waitcnt vmcnt(" #n ")" ::: "memory")
; #define PG8_WAIT_L(n) asm volatile("s_waitcnt lgkmcnt(" #n ")" ::: "memory")
; #define PG8_BAR __builtin_amdgcn_s_barrier()
; #define PG8_SCHED __builtin_amdgcn_sched_barrier(0)
; template <class Epi, class Sched, bool ALIGN_EPI = false, bool SP2 = false>
; __device__ __forceinline__ void gemm_phase(PG8_LAS unsigned char* lds, const Gemm g, const Sched& S, const Epi& E) {
;     ...
;             PG8_LDB(B0, 0, 0); PG8_LDB(B1, 0, 1); PG8_SCHED; PG8_LDA(At, 0, 0); PG8_STAGE(PG8_SA(1, 1), a1 + hstep, voffA);
;             PG8_WAIT_V(8); PG8_WAIT_L(0); PG8_BAR; PG8_MMA(0, 0, At, B0); PG8_MMA(0, 1, At, B1); PG8_BAR; PG8_SCHED;
;             PG8_LDA(At, 0, 1); PG8_STAGE(PG8_SB(0, 0), b2, voffB); PG8_STAGE(PG8_SB(0, 1), b2 + hstep, voffB); PG8_STAGE(PG8_SA(0, 0), a2, voffA);
;             PG8_WAIT_V(8); PG8_WAIT_L(0); PG8_BAR; PG8_MMA(1, 0, At, B0); PG8_MMA(1, 1, At, B1); PG8_BAR; PG8_SCHED;
;     ...
; #pragma unroll
;         for (int a = 0; a < 2; ++a)
; #pragma unroll
;             for (int b = 0; b < 2; ++b)
; #pragma unroll
;                 for (int m = 0; m < 4; ++m)
; #pragma unroll
;                     for (int n = 0; n < 2; ++n) acc[a][b][m][n] = (f32x4){0.f, 0.f, 0.f, 0.f};
;         cur = nxt; cA = nA; cB = nB; ++ui;
.LBB0_1102:
	s_ashr_i32 s13, s12, 31
	s_lshl_b64 s[14:15], s[12:13], 19
	s_add_u32 s14, s74, s14
	s_addc_u32 s15, s75, s15
	s_and_b64 s[20:21], s[6:7], exec
	s_cselect_b32 s13, s15, s5
	s_cselect_b32 s36, s14, s4
	s_ashr_i32 s11, s10, 31
	s_lshl_b64 s[20:21], s[10:11], 19
	s_add_u32 s20, s16, s20
	s_addc_u32 s21, s78, s21
	s_and_b64 s[38:39], s[6:7], exec
	s_cselect_b32 s11, s21, s23
	s_cselect_b32 s37, s20, s22
	s_add_u32 s4, s4, 0x40080
	v_lshl_add_u32 v144, s24, 8, v152
	s_addc_u32 s5, s5, 0
	v_ashrrev_i32_e32 v145, 31, v144
	s_add_u32 s38, s22, 0x100
	v_lshl_add_u64 v[146:147], v[144:145], 2, s[52:53]
	s_addc_u32 s39, s23, 0
	s_mov_b32 s40, -2
	s_waitcnt vmcnt(0)
	s_branch .LBB0_1104
.LpeelC:
	s_add_u32 s24, s4, 0xfffc0080
	s_addc_u32 s25, s5, -1
	s_and_b64 s[22:23], s[22:23], exec
	s_cselect_b32 s25, s13, s25
	s_cselect_b32 s24, s36, s24
	s_cselect_b32 s23, s11, s39
	s_cselect_b32 s22, s37, s38
	s_add_i32 s41, 0, 0x10000
	v_add_u32_e32 v145, s41, v153
	s_add_i32 s46, 0, 0x14000
	ds_read_b128 v[148:151], v145
	ds_read_b128 v[172:175], v145 offset:1024
	ds_read_b128 v[176:179], v145 offset:2048
	ds_read_b128 v[180:183], v145 offset:3072
	v_add_u32_e32 v145, s46, v153
	ds_read_b128 v[184:187], v145
	ds_read_b128 v[188:191], v145 offset:1024
	ds_read_b128 v[192:195], v145 offset:2048
	ds_read_b128 v[196:199], v145 offset:3072
	v_lshl_add_u64 v[220:221], s[4:5], 0, v[140:141]
	s_add_i32 m0, s87, 0xc000
	ds_read_b128 v[200:203], v162
	ds_read_b128 v[204:207], v162 offset:1024
	ds_read_b128 v[208:211], v162 offset:2048
	ds_read_b128 v[212:215], v162 offset:3072
	ds_read_b128 v[216:219], v162 offset:4096
	ds_read_b128 v[236:239], v162 offset:5120
	ds_read_b128 v[240:243], v162 offset:6144
	ds_read_b128 v[244:247], v162 offset:7168
	global_load_lds_dwordx4 v[220:221], off
	v_lshl_add_u64 v[220:221], s[4:5], 0, v[142:143]
	s_add_i32 m0, s87, 0xe000
	s_nop 0
	global_load_lds_dwordx4 v[220:221], off
	s_waitcnt vmcnt(8)
	s_waitcnt lgkmcnt(0)
	s_barrier
	s_setprio 1
	s_waitcnt lgkmcnt(0)
	v_mfma_f32_16x16x32_bf16 v[130:133], v[148:151], v[200:203], 0
	v_mfma_f32_16x16x32_bf16 v[126:129], v[176:179], v[200:203], 0
	v_mfma_f32_16x16x32_bf16 v[114:117], v[148:151], v[208:211], 0
	v_mfma_f32_16x16x32_bf16 v[110:113], v[176:179], v[208:211], 0
	v_mfma_f32_16x16x32_bf16 v[98:101], v[148:151], v[216:219], 0
	v_mfma_f32_16x16x32_bf16 v[94:97], v[176:179], v[216:219], 0
	v_mfma_f32_16x16x32_bf16 v[82:85], v[148:151], v[240:243], 0
	v_mfma_f32_16x16x32_bf16 v[78:81], v[176:179], v[240:243], 0
	v_mfma_f32_16x16x32_bf16 v[130:133], v[172:175], v[204:207], v[130:133]
	v_mfma_f32_16x16x32_bf16 v[126:129], v[180:183], v[204:207], v[126:129]
	v_mfma_f32_16x16x32_bf16 v[114:117], v[172:175], v[212:215], v[114:117]
	v_mfma_f32_16x16x32_bf16 v[110:113], v[180:183], v[212:215], v[110:113]
	v_mfma_f32_16x16x32_bf16 v[98:101], v[172:175], v[236:239], v[98:101]
	v_mfma_f32_16x16x32_bf16 v[94:97], v[180:183], v[236:239], v[94:97]
	v_mfma_f32_16x16x32_bf16 v[82:85], v[172:175], v[244:247], v[82:85]
	v_mfma_f32_16x16x32_bf16 v[78:81], v[180:183], v[244:247], v[78:81]
	s_setprio 0
	s_setprio 1
	v_mfma_f32_16x16x32_bf16 v[122:125], v[184:187], v[200:203], 0
	v_mfma_f32_16x16x32_bf16 v[118:121], v[192:195], v[200:203], 0
	v_mfma_f32_16x16x32_bf16 v[106:109], v[184:187], v[208:211], 0
	v_mfma_f32_16x16x32_bf16 v[102:105], v[192:195], v[208:211], 0
	v_mfma_f32_16x16x32_bf16 v[90:93], v[184:187], v[216:219], 0
	v_mfma_f32_16x16x32_bf16 v[86:89], v[192:195], v[216:219], 0
	v_mfma_f32_16x16x32_bf16 v[74:77], v[184:187], v[240:243], 0
	v_mfma_f32_16x16x32_bf16 v[70:73], v[192:195], v[240:243], 0
	v_mfma_f32_16x16x32_bf16 v[122:125], v[188:191], v[204:207], v[122:125]
	v_mfma_f32_16x16x32_bf16 v[118:121], v[196:199], v[204:207], v[118:121]
	v_mfma_f32_16x16x32_bf16 v[106:109], v[188:191], v[212:215], v[106:109]
	v_mfma_f32_16x16x32_bf16 v[102:105], v[196:199], v[212:215], v[102:105]
	v_mfma_f32_16x16x32_bf16 v[90:93], v[188:191], v[236:239], v[90:93]
	v_mfma_f32_16x16x32_bf16 v[86:89], v[196:199], v[236:239], v[86:89]
	v_mfma_f32_16x16x32_bf16 v[74:77], v[188:191], v[244:247], v[74:77]
	v_mfma_f32_16x16x32_bf16 v[70:73], v[196:199], v[244:247], v[70:73]
	s_setprio 0
	s_barrier
	s_add_i32 s41, s41, s79
	v_lshl_add_u64 v[220:221], s[22:23], 0, v[156:157]
	s_mov_b32 m0, s41
	ds_read_b128 v[200:203], v162 offset:16384
	ds_read_b128 v[204:207], v162 offset:17408
	ds_read_b128 v[208:211], v162 offset:18432
	ds_read_b128 v[212:215], v162 offset:19456
	ds_read_b128 v[216:219], v162 offset:20480
	ds_read_b128 v[236:239], v162 offset:21504
	ds_read_b128 v[240:243], v162 offset:22528
	ds_read_b128 v[244:247], v162 offset:23552
	global_load_lds_dwordx4 v[220:221], off
	s_add_i32 m0, s41, 0x2000
	s_add_u32 s44, s22, 0x40000
	v_lshl_add_u64 v[222:223], s[22:23], 0, v[134:135]
	s_addc_u32 s45, s23, 0
	s_add_i32 s41, s46, s79
	global_load_lds_dwordx4 v[222:223], off
	v_lshl_add_u64 v[226:227], s[44:45], 0, v[156:157]
	s_mov_b32 m0, s41
	v_lshl_add_u64 v[248:249], s[24:25], 0, v[136:137]
	global_load_lds_dwordx4 v[226:227], off
	v_lshl_add_u64 v[226:227], s[44:45], 0, v[134:135]
	s_add_i32 m0, s41, 0x2000
	s_nop 0
	global_load_lds_dwordx4 v[226:227], off
	v_lshl_add_u64 v[226:227], s[24:25], 0, v[138:139]
	s_mov_b32 m0, s87
	s_nop 0
	global_load_lds_dwordx4 v[226:227], off
	s_mov_b32 m0, s19
	s_nop 0
	global_load_lds_dwordx4 v[248:249], off
	s_waitcnt vmcnt(8)
	s_waitcnt lgkmcnt(0)
	s_barrier
; #define PG8_STAGE(bufoff, gbase, voff) do { _Pragma("unroll") for (int _i = 0; _i < 2; ++_i) \
;         __builtin_amdgcn_global_load_lds((const unsigned*)((const char*)(gbase) + (voff)[_i]), (PG8_LAS unsigned*)(lds + (bufoff) + ldsw + _i * 8192), 16, 0, 0); } while (0)
; #define PG8_LDA(dst, b, h) do { _Pragma("unroll") for (int m = 0; m < 4; ++m) _Pragma("unroll") for (int k = 0; k < 2; ++k) dst[m][k] = *(const PG8_LAS bf16x8*)(lds + PG8_SA(b, h) + aoff + m * 2048 + k * 1024); } while (0)
; #define PG8_LDB(dst, b, h) do { _Pragma("unroll") for (int n = 0; n < 2; ++n) _Pragma("unroll") for (int k = 0; k < 2; ++k) dst[n][k] = *(const PG8_LAS bf16x8*)(lds + PG8_SB(b, h) + boff + n * 2048 + k * 1024); } while (0)
; #define PG8_MMA(ai, bj, At, Bt) do { __builtin_amdgcn_s_setprio(1); _Pragma("unroll") for (int m = 0; m < 4; ++m) _Pragma("unroll") for (int n = 0; n < 2; ++n) _Pragma("unroll") for (int k = 0; k < 2; ++k) \
;         acc[ai][bj][m][n] = __builtin_amdgcn_mfma_f32_16x16x32_bf16(Bt[n][k], At[m][k], acc[ai][bj][m][n], 0, 0, 0); __builtin_amdgcn_s_setprio(0); } while (0)
; #define PG8_WAIT_V(n) asm volatile("s_waitcnt vmcnt(" #n ")" ::: "memory")
; #define PG8_WAIT_L(n) asm volatile("s_waitcnt lgkmcnt(" #n ")" ::: "memory")
; #define PG8_BAR __builtin_amdgcn_s_barrier()
; #define PG8_SCHED __builtin_amdgcn_sched_barrier(0)
; template <class Epi, class Sched, bool ALIGN_EPI = false, bool SP2 = false>
; __device__ __forceinline__ void gemm_phase(PG8_LAS unsigned char* lds, const Gemm g, const Sched& S, const Epi& E) {
;     ...
;             PG8_LDB(B0, 0, 0); PG8_LDB(B1, 0, 1); PG8_SCHED; PG8_LDA(At, 0, 0); PG8_STAGE(PG8_SA(1, 1), a1 + hstep, voffA);
;             PG8_WAIT_V(8); PG8_WAIT_L(0); PG8_BAR; PG8_MMA(0, 0, At, B0); PG8_MMA(0, 1, At, B1); PG8_BAR; PG8_SCHED;
;             PG8_LDA(At, 0, 1); PG8_STAGE(PG8_SB(0, 0), b2, voffB); PG8_STAGE(PG8_SB(0, 1), b2 + hstep, voffB); PG8_STAGE(PG8_SA(0, 0), a2, voffA);
;             PG8_WAIT_V(8); PG8_WAIT_L(0); PG8_BAR; PG8_MMA(1, 0, At, B0); PG8_MMA(1, 1, At, B1); PG8_BAR; PG8_SCHED;
	s_setprio 1
	s_waitcnt lgkmcnt(0)
	v_mfma_f32_16x16x32_bf16 v[66:69], v[148:151], v[200:203], 0
	v_mfma_f32_16x16x32_bf16 v[62:65], v[176:179], v[200:203], 0
	v_mfma_f32_16x16x32_bf16 v[50:53], v[148:151], v[208:211], 0
	v_mfma_f32_16x16x32_bf16 v[46:49], v[176:179], v[208:211], 0
	v_mfma_f32_16x16x32_bf16 v[34:37], v[148:151], v[216:219], 0
	v_mfma_f32_16x16x32_bf16 v[30:33], v[176:179], v[216:219], 0
	v_mfma_f32_16x16x32_bf16 v[18:21], v[148:151], v[240:243], 0
	v_mfma_f32_16x16x32_bf16 v[14:17], v[176:179], v[240:243], 0
	v_mfma_f32_16x16x32_bf16 v[66:69], v[172:175], v[204:207], v[66:69]
	v_mfma_f32_16x16x32_bf16 v[62:65], v[180:183], v[204:207], v[62:65]
	v_mfma_f32_16x16x32_bf16 v[50:53], v[172:175], v[212:215], v[50:53]
	v_mfma_f32_16x16x32_bf16 v[46:49], v[180:183], v[212:215], v[46:49]
	v_mfma_f32_16x16x32_bf16 v[34:37], v[172:175], v[236:239], v[34:37]
	v_mfma_f32_16x16x32_bf16 v[30:33], v[180:183], v[236:239], v[30:33]
	v_mfma_f32_16x16x32_bf16 v[18:21], v[172:175], v[244:247], v[18:21]
	v_mfma_f32_16x16x32_bf16 v[14:17], v[180:183], v[244:247], v[14:17]
	s_setprio 0
	s_setprio 1
	v_mfma_f32_16x16x32_bf16 v[58:61], v[184:187], v[200:203], 0
	v_mfma_f32_16x16x32_bf16 v[54:57], v[192:195], v[200:203], 0
	v_mfma_f32_16x16x32_bf16 v[42:45], v[184:187], v[208:211], 0
	v_mfma_f32_16x16x32_bf16 v[38:41], v[192:195], v[208:211], 0
	v_mfma_f32_16x16x32_bf16 v[26:29], v[184:187], v[216:219], 0
	v_mfma_f32_16x16x32_bf16 v[22:25], v[192:195], v[216:219], 0
	v_mfma_f32_16x16x32_bf16 v[10:13], v[184:187], v[240:243], 0
	v_mfma_f32_16x16x32_bf16 v[6:9], v[192:195], v[240:243], 0
	v_mfma_f32_16x16x32_bf16 v[58:61], v[188:191], v[204:207], v[58:61]
	v_mfma_f32_16x16x32_bf16 v[54:57], v[196:199], v[204:207], v[54:57]
	v_mfma_f32_16x16x32_bf16 v[42:45], v[188:191], v[212:215], v[42:45]
	v_mfma_f32_16x16x32_bf16 v[38:41], v[196:199], v[212:215], v[38:41]
	v_mfma_f32_16x16x32_bf16 v[26:29], v[188:191], v[236:239], v[26:29]
	v_mfma_f32_16x16x32_bf16 v[22:25], v[196:199], v[236:239], v[22:25]
	v_mfma_f32_16x16x32_bf16 v[10:13], v[188:191], v[244:247], v[10:13]
	v_mfma_f32_16x16x32_bf16 v[6:9], v[196:199], v[244:247], v[6:9]
	s_setprio 0
	s_barrier
	s_branch .LpeelC_mid
.LBB0_1103:
	s_cmp_eq_u32 s40, -2
	s_cbranch_scc1 .LpeelC
	s_add_u32 s24, s4, 0xfffc0080
	s_addc_u32 s25, s5, -1
	s_and_b64 s[22:23], s[22:23], exec
	s_cselect_b32 s25, s13, s25
	s_cselect_b32 s24, s36, s24
	s_cselect_b32 s23, s11, s39
	s_cselect_b32 s22, s37, s38
	s_add_i32 s41, 0, 0x10000
	v_add_u32_e32 v145, s41, v153
	s_add_i32 s46, 0, 0x14000
	ds_read_b128 v[148:151], v145
	ds_read_b128 v[172:175], v145 offset:1024
	ds_read_b128 v[176:179], v145 offset:2048
	ds_read_b128 v[180:183], v145 offset:3072
	v_add_u32_e32 v145, s46, v153
	ds_read_b128 v[184:187], v145
	ds_read_b128 v[188:191], v145 offset:1024
	ds_read_b128 v[192:195], v145 offset:2048
	ds_read_b128 v[196:199], v145 offset:3072
	v_lshl_add_u64 v[220:221], s[4:5], 0, v[140:141]
	s_add_i32 m0, s87, 0xc000
	ds_read_b128 v[200:203], v162
	ds_read_b128 v[204:207], v162 offset:1024
	ds_read_b128 v[208:211], v162 offset:2048
	ds_read_b128 v[212:215], v162 offset:3072
	ds_read_b128 v[216:219], v162 offset:4096
	ds_read_b128 v[236:239], v162 offset:5120
	ds_read_b128 v[240:243], v162 offset:6144
	ds_read_b128 v[244:247], v162 offset:7168
	global_load_lds_dwordx4 v[220:221], off
	v_lshl_add_u64 v[220:221], s[4:5], 0, v[142:143]
	s_add_i32 m0, s87, 0xe000
	s_nop 0
	global_load_lds_dwordx4 v[220:221], off
	s_waitcnt vmcnt(8)
	s_waitcnt lgkmcnt(0)
	s_barrier
	s_setprio 1
	s_waitcnt lgkmcnt(0)
	v_mfma_f32_16x16x32_bf16 v[130:133], v[148:151], v[200:203], v[130:133]
	v_mfma_f32_16x16x32_bf16 v[126:129], v[176:179], v[200:203], v[126:129]
	v_mfma_f32_16x16x32_bf16 v[114:117], v[148:151], v[208:211], v[114:117]
	v_mfma_f32_16x16x32_bf16 v[110:113], v[176:179], v[208:211], v[110:113]
	v_mfma_f32_16x16x32_bf16 v[98:101], v[148:151], v[216:219], v[98:101]
	v_mfma_f32_16x16x32_bf16 v[94:97], v[176:179], v[216:219], v[94:97]
	v_mfma_f32_16x16x32_bf16 v[82:85], v[148:151], v[240:243], v[82:85]
	v_mfma_f32_16x16x32_bf16 v[78:81], v[176:179], v[240:243], v[78:81]
	v_mfma_f32_16x16x32_bf16 v[130:133], v[172:175], v[204:207], v[130:133]
	v_mfma_f32_16x16x32_bf16 v[126:129], v[180:183], v[204:207], v[126:129]
	v_mfma_f32_16x16x32_bf16 v[114:117], v[172:175], v[212:215], v[114:117]
	v_mfma_f32_16x16x32_bf16 v[110:113], v[180:183], v[212:215], v[110:113]
	v_mfma_f32_16x16x32_bf16 v[98:101], v[172:175], v[236:239], v[98:101]
	v_mfma_f32_16x16x32_bf16 v[94:97], v[180:183], v[236:239], v[94:97]
	v_mfma_f32_16x16x32_bf16 v[82:85], v[172:175], v[244:247], v[82:85]
	v_mfma_f32_16x16x32_bf16 v[78:81], v[180:183], v[244:247], v[78:81]
	s_setprio 0
	s_setprio 1
	v_mfma_f32_16x16x32_bf16 v[122:125], v[184:187], v[200:203], v[122:125]
	v_mfma_f32_16x16x32_bf16 v[118:121], v[192:195], v[200:203], v[118:121]
	v_mfma_f32_16x16x32_bf16 v[106:109], v[184:187], v[208:211], v[106:109]
	v_mfma_f32_16x16x32_bf16 v[102:105], v[192:195], v[208:211], v[102:105]
	v_mfma_f32_16x16x32_bf16 v[90:93], v[184:187], v[216:219], v[90:93]
	v_mfma_f32_16x16x32_bf16 v[86:89], v[192:195], v[216:219], v[86:89]
	v_mfma_f32_16x16x32_bf16 v[74:77], v[184:187], v[240:243], v[74:77]
	v_mfma_f32_16x16x32_bf16 v[70:73], v[192:195], v[240:243], v[70:73]
	v_mfma_f32_16x16x32_bf16 v[122:125], v[188:191], v[204:207], v[122:125]
	v_mfma_f32_16x16x32_bf16 v[118:121], v[196:199], v[204:207], v[118:121]
	v_mfma_f32_16x16x32_bf16 v[106:109], v[188:191], v[212:215], v[106:109]
	v_mfma_f32_16x16x32_bf16 v[102:105], v[196:199], v[212:215], v[102:105]
	v_mfma_f32_16x16x32_bf16 v[90:93], v[188:191], v[236:239], v[90:93]
	v_mfma_f32_16x16x32_bf16 v[86:89], v[196:199], v[236:239], v[86:89]
	v_mfma_f32_16x16x32_bf16 v[74:77], v[188:191], v[244:247], v[74:77]
	v_mfma_f32_16x16x32_bf16 v[70:73], v[196:199], v[244:247], v[70:73]
	s_setprio 0
	s_barrier
; #define PG8_STAGE(bufoff, gbase, voff) do { _Pragma("unroll") for (int _i = 0; _i < 2; ++_i) \
;         __builtin_amdgcn_global_load_lds((const unsigned*)((const char*)(gbase) + (voff)[_i]), (PG8_LAS unsigned*)(lds + (bufoff) + ldsw + _i * 8192), 16, 0, 0); } while (0)
; #define PG8_LDA(dst, b, h) do { _Pragma("unroll") for (int m = 0; m < 4; ++m) _Pragma("unroll") for (int k = 0; k < 2; ++k) dst[m][k] = *(const PG8_LAS bf16x8*)(lds + PG8_SA(b, h) + aoff + m * 2048 + k * 1024); } while (0)
; #define PG8_LDB(dst, b, h) do { _Pragma("unroll") for (int n = 0; n < 2; ++n) _Pragma("unroll") for (int k = 0; k < 2; ++k) dst[n][k] = *(const PG8_LAS bf16x8*)(lds + PG8_SB(b, h) + boff + n * 2048 + k * 1024); } while (0)
; #define PG8_MMA(ai, bj, At, Bt) do { __builtin_amdgcn_s_setprio(1); _Pragma("unroll") for (int m = 0; m < 4; ++m) _Pragma("unroll") for (int n = 0; n < 2; ++n) _Pragma("unroll") for (int k = 0; k < 2; ++k) \
;         acc[ai][bj][m][n] = __builtin_amdgcn_mfma_f32_16x16x32_bf16(Bt[n][k], At[m][k], acc[ai][bj][m][n], 0, 0, 0); __builtin_amdgcn_s_setprio(0); } while (0)
; #define PG8_WAIT_V(n) asm volatile("s_waitcnt vmcnt(" #n ")" ::: "memory")
; #define PG8_WAIT_L(n) asm volatile("s_waitcnt lgkmcnt(" #n ")" ::: "memory")
; #define PG8_BAR __builtin_amdgcn_s_barrier()
; #define PG8_SCHED __builtin_amdgcn_sched_barrier(0)
; template <class Epi, class Sched, bool ALIGN_EPI = false, bool SP2 = false>
; __device__ __forceinline__ void gemm_phase(PG8_LAS unsigned char* lds, const Gemm g, const Sched& S, const Epi& E) {
;     ...
;             PG8_LDA(At, 0, 1); PG8_STAGE(PG8_SB(0, 0), b2, voffB); PG8_STAGE(PG8_SB(0, 1), b2 + hstep, voffB); PG8_STAGE(PG8_SA(0, 0), a2, voffA);
;             PG8_WAIT_V(8); PG8_WAIT_L(0); PG8_BAR; PG8_MMA(1, 0, At, B0); PG8_MMA(1, 1, At, B1); PG8_BAR; PG8_SCHED;
;             PG8_LDB(B0, 1, 0); PG8_LDB(B1, 1, 1); PG8_SCHED; PG8_LDA(At, 1, 0); PG8_STAGE(PG8_SA(0, 1), a2 + hstep, voffA);
;             PG8_WAIT_V(8); PG8_WAIT_L(0); PG8_BAR; PG8_MMA(0, 0, At, B0); PG8_MMA(0, 1, At, B1); PG8_BAR; PG8_SCHED;
	s_add_i32 s41, s41, s79
	v_lshl_add_u64 v[220:221], s[22:23], 0, v[156:157]
	s_mov_b32 m0, s41
	ds_read_b128 v[200:203], v162 offset:16384
	ds_read_b128 v[204:207], v162 offset:17408
	ds_read_b128 v[208:211], v162 offset:18432
	ds_read_b128 v[212:215], v162 offset:19456
	ds_read_b128 v[216:219], v162 offset:20480
	ds_read_b128 v[236:239], v162 offset:21504
	ds_read_b128 v[240:243], v162 offset:22528
	ds_read_b128 v[244:247], v162 offset:23552
	global_load_lds_dwordx4 v[220:221], off
	s_add_i32 m0, s41, 0x2000
	s_add_u32 s44, s22, 0x40000
	v_lshl_add_u64 v[222:223], s[22:23], 0, v[134:135]
	s_addc_u32 s45, s23, 0
	s_add_i32 s41, s46, s79
	global_load_lds_dwordx4 v[222:223], off
	v_lshl_add_u64 v[226:227], s[44:45], 0, v[156:157]
	s_mov_b32 m0, s41
	v_lshl_add_u64 v[248:249], s[24:25], 0, v[136:137]
	global_load_lds_dwordx4 v[226:227], off
	v_lshl_add_u64 v[226:227], s[44:45], 0, v[134:135]
	s_add_i32 m0, s41, 0x2000
	s_nop 0
	global_load_lds_dwordx4 v[226:227], off
	v_lshl_add_u64 v[226:227], s[24:25], 0, v[138:139]
	s_mov_b32 m0, s87
	s_nop 0
	global_load_lds_dwordx4 v[226:227], off
	s_mov_b32 m0, s19
	s_nop 0
	global_load_lds_dwordx4 v[248:249], off
	s_waitcnt vmcnt(8)
	s_waitcnt lgkmcnt(0)
	s_barrier
	s_setprio 1
	s_waitcnt lgkmcnt(0)
	v_mfma_f32_16x16x32_bf16 v[66:69], v[148:151], v[200:203], v[66:69]
	v_mfma_f32_16x16x32_bf16 v[62:65], v[176:179], v[200:203], v[62:65]
	v_mfma_f32_16x16x32_bf16 v[50:53], v[148:151], v[208:211], v[50:53]
	v_mfma_f32_16x16x32_bf16 v[46:49], v[176:179], v[208:211], v[46:49]
	v_mfma_f32_16x16x32_bf16 v[34:37], v[148:151], v[216:219], v[34:37]
	v_mfma_f32_16x16x32_bf16 v[30:33], v[176:179], v[216:219], v[30:33]
	v_mfma_f32_16x16x32_bf16 v[18:21], v[148:151], v[240:243], v[18:21]
	v_mfma_f32_16x16x32_bf16 v[14:17], v[176:179], v[240:243], v[14:17]
	v_mfma_f32_16x16x32_bf16 v[66:69], v[172:175], v[204:207], v[66:69]
	v_mfma_f32_16x16x32_bf16 v[62:65], v[180:183], v[204:207], v[62:65]
	v_mfma_f32_16x16x32_bf16 v[50:53], v[172:175], v[212:215], v[50:53]
	v_mfma_f32_16x16x32_bf16 v[46:49], v[180:183], v[212:215], v[46:49]
	v_mfma_f32_16x16x32_bf16 v[34:37], v[172:175], v[236:239], v[34:37]
	v_mfma_f32_16x16x32_bf16 v[30:33], v[180:183], v[236:239], v[30:33]
	v_mfma_f32_16x16x32_bf16 v[18:21], v[172:175], v[244:247], v[18:21]
	v_mfma_f32_16x16x32_bf16 v[14:17], v[180:183], v[244:247], v[14:17]
	s_setprio 0
	s_setprio 1
	v_mfma_f32_16x16x32_bf16 v[58:61], v[184:187], v[200:203], v[58:61]
	v_mfma_f32_16x16x32_bf16 v[54:57], v[192:195], v[200:203], v[54:57]
	v_mfma_f32_16x16x32_bf16 v[42:45], v[184:187], v[208:211], v[42:45]
	v_mfma_f32_16x16x32_bf16 v[38:41], v[192:195], v[208:211], v[38:41]
	v_mfma_f32_16x16x32_bf16 v[26:29], v[184:187], v[216:219], v[26:29]
	v_mfma_f32_16x16x32_bf16 v[22:25], v[192:195], v[216:219], v[22:25]
	v_mfma_f32_16x16x32_bf16 v[10:13], v[184:187], v[240:243], v[10:13]
	v_mfma_f32_16x16x32_bf16 v[6:9], v[192:195], v[240:243], v[6:9]
	v_mfma_f32_16x16x32_bf16 v[58:61], v[188:191], v[204:207], v[58:61]
	v_mfma_f32_16x16x32_bf16 v[54:57], v[196:199], v[204:207], v[54:57]
	v_mfma_f32_16x16x32_bf16 v[42:45], v[188:191], v[212:215], v[42:45]
	v_mfma_f32_16x16x32_bf16 v[38:41], v[196:199], v[212:215], v[38:41]
	v_mfma_f32_16x16x32_bf16 v[26:29], v[188:191], v[236:239], v[26:29]
	v_mfma_f32_16x16x32_bf16 v[22:25], v[196:199], v[236:239], v[22:25]
	v_mfma_f32_16x16x32_bf16 v[10:13], v[188:191], v[244:247], v[10:13]
	v_mfma_f32_16x16x32_bf16 v[6:9], v[196:199], v[244:247], v[6:9]
	s_setprio 0
	s_barrier
.LpeelC_mid:
	s_add_i32 s41, 0, 0x18000
	v_add_u32_e32 v145, s41, v153
	s_add_i32 s44, 0, 0x1c000
	ds_read_b128 v[148:151], v145
	ds_read_b128 v[172:175], v145 offset:1024
	ds_read_b128 v[176:179], v145 offset:2048
	ds_read_b128 v[180:183], v145 offset:3072
	v_add_u32_e32 v145, s44, v153
	ds_read_b128 v[184:187], v145
	ds_read_b128 v[188:191], v145 offset:1024
	ds_read_b128 v[192:195], v145 offset:2048
	ds_read_b128 v[196:199], v145 offset:3072
	s_add_u32 s24, s24, 0x40000
	s_addc_u32 s25, s25, 0
	s_mov_b32 m0, s88
	v_lshl_add_u64 v[250:251], s[24:25], 0, v[138:139]
	ds_read_b128 v[200:203], v162 offset:32768
	ds_read_b128 v[204:207], v162 offset:33792
	ds_read_b128 v[208:211], v162 offset:34816
	ds_read_b128 v[212:215], v162 offset:35840
	ds_read_b128 v[216:219], v162 offset:36864
	ds_read_b128 v[236:239], v162 offset:37888
	ds_read_b128 v[240:243], v162 offset:38912
	ds_read_b128 v[244:247], v162 offset:39936
	global_load_lds_dwordx4 v[250:251], off
	v_lshl_add_u64 v[250:251], s[24:25], 0, v[136:137]
	s_mov_b32 m0, s89
	s_nop 0
	global_load_lds_dwordx4 v[250:251], off
	s_waitcnt vmcnt(8)
	s_waitcnt lgkmcnt(0)
	s_barrier
; #define PG8_STAGE(bufoff, gbase, voff) do { _Pragma("unroll") for (int _i = 0; _i < 2; ++_i) \
;         __builtin_amdgcn_global_load_lds((const unsigned*)((const char*)(gbase) + (voff)[_i]), (PG8_LAS unsigned*)(lds + (bufoff) + ldsw + _i * 8192), 16, 0, 0); } while (0)
; #define PG8_LDA(dst, b, h) do { _Pragma("unroll") for (int m = 0; m < 4; ++m) _Pragma("unroll") for (int k = 0; k < 2; ++k) dst[m][k] = *(const PG8_LAS bf16x8*)(lds + PG8_SA(b, h) + aoff + m * 2048 + k * 1024); } while (0)
; #define PG8_MMA(ai, bj, At, Bt) do { __builtin_amdgcn_s_setprio(1); _Pragma("unroll") for (int m = 0; m < 4; ++m) _Pragma("unroll") for (int n = 0; n < 2; ++n) _Pragma("unroll") for (int k = 0; k < 2; ++k) \
;         acc[ai][bj][m][n] = __builtin_amdgcn_mfma_f32_16x16x32_bf16(Bt[n][k], At[m][k], acc[ai][bj][m][n], 0, 0, 0); __builtin_amdgcn_s_setprio(0); } while (0)
; #define PG8_WAIT_V(n) asm volatile("s_waitcnt vmcnt(" #n ")" ::: "memory")
; #define PG8_WAIT_L(n) asm volatile("s_waitcnt lgkmcnt(" #n ")" ::: "memory")
; #define PG8_BAR __builtin_amdgcn_s_barrier()
; #define PG8_SCHED __builtin_amdgcn_sched_barrier(0)
; template <class Epi, class Sched, bool ALIGN_EPI = false, bool SP2 = false>
; __device__ __forceinline__ void gemm_phase(PG8_LAS unsigned char* lds, const Gemm g, const Sched& S, const Epi& E) {
;     ...
;             PG8_WAIT_V(8); PG8_WAIT_L(0); PG8_BAR; PG8_MMA(0, 0, At, B0); PG8_MMA(0, 1, At, B1); PG8_BAR; PG8_SCHED;
;             PG8_LDA(At, 1, 1); PG8_STAGE(PG8_SB(1, 0), b3, voffB); PG8_STAGE(PG8_SB(1, 1), b3 + hstep, voffB); PG8_STAGE(PG8_SA(1, 0), a3, voffA);
;             PG8_WAIT_V(8); PG8_WAIT_L(0); PG8_BAR; PG8_MMA(1, 0, At, B0); PG8_MMA(1, 1, At, B1); PG8_BAR; PG8_SCHED;
	s_setprio 1
	s_waitcnt lgkmcnt(0)
	v_mfma_f32_16x16x32_bf16 v[130:133], v[148:151], v[200:203], v[130:133]
	v_mfma_f32_16x16x32_bf16 v[126:129], v[176:179], v[200:203], v[126:129]
	v_mfma_f32_16x16x32_bf16 v[114:117], v[148:151], v[208:211], v[114:117]
	v_mfma_f32_16x16x32_bf16 v[110:113], v[176:179], v[208:211], v[110:113]
	v_mfma_f32_16x16x32_bf16 v[98:101], v[148:151], v[216:219], v[98:101]
	v_mfma_f32_16x16x32_bf16 v[94:97], v[176:179], v[216:219], v[94:97]
	v_mfma_f32_16x16x32_bf16 v[82:85], v[148:151], v[240:243], v[82:85]
	v_mfma_f32_16x16x32_bf16 v[78:81], v[176:179], v[240:243], v[78:81]
	v_mfma_f32_16x16x32_bf16 v[130:133], v[172:175], v[204:207], v[130:133]
	v_mfma_f32_16x16x32_bf16 v[126:129], v[180:183], v[204:207], v[126:129]
	v_mfma_f32_16x16x32_bf16 v[114:117], v[172:175], v[212:215], v[114:117]
	v_mfma_f32_16x16x32_bf16 v[110:113], v[180:183], v[212:215], v[110:113]
	v_mfma_f32_16x16x32_bf16 v[98:101], v[172:175], v[236:239], v[98:101]
	v_mfma_f32_16x16x32_bf16 v[94:97], v[180:183], v[236:239], v[94:97]
	v_mfma_f32_16x16x32_bf16 v[82:85], v[172:175], v[244:247], v[82:85]
	v_mfma_f32_16x16x32_bf16 v[78:81], v[180:183], v[244:247], v[78:81]
	s_setprio 0
	s_setprio 1
	v_mfma_f32_16x16x32_bf16 v[122:125], v[184:187], v[200:203], v[122:125]
	v_mfma_f32_16x16x32_bf16 v[118:121], v[192:195], v[200:203], v[118:121]
	v_mfma_f32_16x16x32_bf16 v[106:109], v[184:187], v[208:211], v[106:109]
	v_mfma_f32_16x16x32_bf16 v[102:105], v[192:195], v[208:211], v[102:105]
	v_mfma_f32_16x16x32_bf16 v[90:93], v[184:187], v[216:219], v[90:93]
	v_mfma_f32_16x16x32_bf16 v[86:89], v[192:195], v[216:219], v[86:89]
	v_mfma_f32_16x16x32_bf16 v[74:77], v[184:187], v[240:243], v[74:77]
	v_mfma_f32_16x16x32_bf16 v[70:73], v[192:195], v[240:243], v[70:73]
	v_mfma_f32_16x16x32_bf16 v[122:125], v[188:191], v[204:207], v[122:125]
	v_mfma_f32_16x16x32_bf16 v[118:121], v[196:199], v[204:207], v[118:121]
	v_mfma_f32_16x16x32_bf16 v[106:109], v[188:191], v[212:215], v[106:109]
	v_mfma_f32_16x16x32_bf16 v[102:105], v[196:199], v[212:215], v[102:105]
	v_mfma_f32_16x16x32_bf16 v[90:93], v[188:191], v[236:239], v[90:93]
	v_mfma_f32_16x16x32_bf16 v[86:89], v[196:199], v[236:239], v[86:89]
	v_mfma_f32_16x16x32_bf16 v[74:77], v[188:191], v[244:247], v[74:77]
	v_mfma_f32_16x16x32_bf16 v[70:73], v[196:199], v[244:247], v[70:73]
	s_setprio 0
	s_barrier
	s_add_i32 s24, s41, s79
	v_lshl_add_u64 v[220:221], v[220:221], 0, s[68:69]
	s_mov_b32 m0, s24
	ds_read_b128 v[200:203], v162 offset:49152
	ds_read_b128 v[204:207], v162 offset:50176
	ds_read_b128 v[208:211], v162 offset:51200
	ds_read_b128 v[212:215], v162 offset:52224
	ds_read_b128 v[216:219], v162 offset:53248
	ds_read_b128 v[236:239], v162 offset:54272
	ds_read_b128 v[240:243], v162 offset:55296
	ds_read_b128 v[244:247], v162 offset:56320
	global_load_lds_dwordx4 v[220:221], off
	s_add_i32 m0, s24, 0x2000
	s_add_u32 s22, s22, 0x40080
	v_lshl_add_u64 v[220:221], v[222:223], 0, s[68:69]
	s_addc_u32 s23, s23, 0
	s_add_i32 s24, s44, s79
	global_load_lds_dwordx4 v[220:221], off
	v_lshl_add_u64 v[220:221], s[22:23], 0, v[156:157]
	s_mov_b32 m0, s24
	s_nop 0
	global_load_lds_dwordx4 v[220:221], off
	v_lshl_add_u64 v[220:221], s[22:23], 0, v[134:135]
	s_add_i32 m0, s24, 0x2000
	s_nop 0
	global_load_lds_dwordx4 v[220:221], off
	v_lshl_add_u64 v[220:221], v[226:227], 0, s[68:69]
	s_mov_b32 m0, s33
	s_nop 0
	global_load_lds_dwordx4 v[220:221], off
	v_lshl_add_u64 v[220:221], v[248:249], 0, s[68:69]
	s_mov_b32 m0, s90
	s_nop 0
	global_load_lds_dwordx4 v[220:221], off
	s_waitcnt vmcnt(8)
	s_waitcnt lgkmcnt(0)
	s_barrier
	s_setprio 1
	s_waitcnt lgkmcnt(0)
	v_mfma_f32_16x16x32_bf16 v[66:69], v[148:151], v[200:203], v[66:69]
	v_mfma_f32_16x16x32_bf16 v[62:65], v[176:179], v[200:203], v[62:65]
	v_mfma_f32_16x16x32_bf16 v[50:53], v[148:151], v[208:211], v[50:53]
	v_mfma_f32_16x16x32_bf16 v[46:49], v[176:179], v[208:211], v[46:49]
	v_mfma_f32_16x16x32_bf16 v[34:37], v[148:151], v[216:219], v[34:37]
	v_mfma_f32_16x16x32_bf16 v[30:33], v[176:179], v[216:219], v[30:33]
	v_mfma_f32_16x16x32_bf16 v[18:21], v[148:151], v[240:243], v[18:21]
	v_mfma_f32_16x16x32_bf16 v[14:17], v[176:179], v[240:243], v[14:17]
	v_mfma_f32_16x16x32_bf16 v[66:69], v[172:175], v[204:207], v[66:69]
	v_mfma_f32_16x16x32_bf16 v[62:65], v[180:183], v[204:207], v[62:65]
	v_mfma_f32_16x16x32_bf16 v[50:53], v[172:175], v[212:215], v[50:53]
	v_mfma_f32_16x16x32_bf16 v[46:49], v[180:183], v[212:215], v[46:49]
	v_mfma_f32_16x16x32_bf16 v[34:37], v[172:175], v[236:239], v[34:37]
	v_mfma_f32_16x16x32_bf16 v[30:33], v[180:183], v[236:239], v[30:33]
	v_mfma_f32_16x16x32_bf16 v[18:21], v[172:175], v[244:247], v[18:21]
	v_mfma_f32_16x16x32_bf16 v[14:17], v[180:183], v[244:247], v[14:17]
	s_setprio 0
	s_setprio 1
	v_mfma_f32_16x16x32_bf16 v[58:61], v[184:187], v[200:203], v[58:61]
	v_mfma_f32_16x16x32_bf16 v[54:57], v[192:195], v[200:203], v[54:57]
	v_mfma_f32_16x16x32_bf16 v[42:45], v[184:187], v[208:211], v[42:45]
	v_mfma_f32_16x16x32_bf16 v[38:41], v[192:195], v[208:211], v[38:41]
	v_mfma_f32_16x16x32_bf16 v[26:29], v[184:187], v[216:219], v[26:29]
	v_mfma_f32_16x16x32_bf16 v[22:25], v[192:195], v[216:219], v[22:25]
	v_mfma_f32_16x16x32_bf16 v[10:13], v[184:187], v[240:243], v[10:13]
	v_mfma_f32_16x16x32_bf16 v[6:9], v[192:195], v[240:243], v[6:9]
	v_mfma_f32_16x16x32_bf16 v[58:61], v[188:191], v[204:207], v[58:61]
	v_mfma_f32_16x16x32_bf16 v[54:57], v[196:199], v[204:207], v[54:57]
	v_mfma_f32_16x16x32_bf16 v[42:45], v[188:191], v[212:215], v[42:45]
	v_mfma_f32_16x16x32_bf16 v[38:41], v[196:199], v[212:215], v[38:41]
	v_mfma_f32_16x16x32_bf16 v[26:29], v[188:191], v[236:239], v[26:29]
	v_mfma_f32_16x16x32_bf16 v[22:25], v[196:199], v[236:239], v[22:25]
	v_mfma_f32_16x16x32_bf16 v[10:13], v[188:191], v[244:247], v[10:13]
	v_mfma_f32_16x16x32_bf16 v[6:9], v[196:199], v[244:247], v[6:9]
	s_setprio 0
	s_barrier
	s_add_i32 s40, s40, 2
	s_add_u32 s4, s4, 0x100
	s_addc_u32 s5, s5, 0
	s_add_u32 s38, s38, 0x100
	s_addc_u32 s39, s39, 0
	s_cmp_gt_u32 s40, 13
	s_cbranch_scc1 .LBB0_1106

; #define PG8_STAGE(bufoff, gbase, voff) do { _Pragma("unroll") for (int _i = 0; _i < 2; ++_i) \
;         __builtin_amdgcn_global_load_lds((const unsigned*)((const char*)(gbase) + (voff)[_i]), (PG8_LAS unsigned*)(lds + (bufoff) + ldsw + _i * 8192), 16, 0, 0); } while (0)
; #define PG8_LDA(dst, b, h) do { _Pragma("unroll") for (int m = 0; m < 4; ++m) _Pragma("unroll") for (int k = 0; k < 2; ++k) dst[m][k] = *(const PG8_LAS bf16x8*)(lds + PG8_SA(b, h) + aoff + m * 2048 + k * 1024); } while (0)
; #define PG8_LDB(dst, b, h) do { _Pragma("unroll") for (int n = 0; n < 2; ++n) _Pragma("unroll") for (int k = 0; k < 2; ++k) dst[n][k] = *(const PG8_LAS bf16x8*)(lds + PG8_SB(b, h) + boff + n * 2048 + k * 1024); } while (0)
; #define PG8_MMA(ai, bj, At, Bt) do { __builtin_amdgcn_s_setprio(1); _Pragma("unroll") for (int m = 0; m < 4; ++m) _Pragma("unroll") for (int n = 0; n < 2; ++n) _Pragma("unroll") for (int k = 0; k < 2; ++k) \
;         acc[ai][bj][m][n] = __builtin_amdgcn_mfma_f32_16x16x32_bf16(Bt[n][k], At[m][k], acc[ai][bj][m][n], 0, 0, 0); __builtin_amdgcn_s_setprio(0); } while (0)
; #define PG8_WAIT_V(n) asm volatile("s_waitcnt vmcnt(" #n ")" ::: "memory")
; #define PG8_WAIT_L(n) asm volatile("s_waitcnt lgkmcnt(" #n ")" ::: "memory")
; #define PG8_BAR __builtin_amdgcn_s_barrier()
; #define PG8_SCHED __builtin_amdgcn_sched_barrier(0)
; template <class Epi, class Sched, bool ALIGN_EPI = false, bool SP2 = false>
; __device__ __forceinline__ void gemm_phase(PG8_LAS unsigned char* lds, const Gemm g, const Sched& S, const Epi& E) {
;     ...
;             PG8_LDB(B0, 0, 0); PG8_LDB(B1, 0, 1); PG8_SCHED; PG8_LDA(At, 0, 0); PG8_STAGE(PG8_SA(1, 1), a1 + hstep, voffA);
;             PG8_WAIT_V(8); PG8_WAIT_L(0); PG8_BAR; PG8_MMA(0, 0, At, B0); PG8_MMA(0, 1, At, B1); PG8_BAR; PG8_SCHED;
;             PG8_LDA(At, 0, 1); PG8_STAGE(PG8_SB(0, 0), b2, voffB); PG8_STAGE(PG8_SB(0, 1), b2 + hstep, voffB); PG8_STAGE(PG8_SA(0, 0), a2, voffA);
;             PG8_WAIT_V(8); PG8_WAIT_L(0); PG8_BAR; PG8_MMA(1, 0, At, B0); PG8_MMA(1, 1, At, B1); PG8_BAR; PG8_SCHED;
;     ...
; #pragma unroll
;         for (int a = 0; a < 2; ++a)
; #pragma unroll
;             for (int b = 0; b < 2; ++b)
; #pragma unroll
;                 for (int m = 0; m < 4; ++m)
; #pragma unroll
;                     for (int n = 0; n < 2; ++n) acc[a][b][m][n] = (f32x4){0.f, 0.f, 0.f, 0.f};
;         cur = nxt; cA = nA; cB = nB; ++ui;
.LBB0_1180:
	s_add_u32 s38, s10, 0x100
	s_addc_u32 s39, s11, 0
	s_mov_b32 s40, -2
	s_waitcnt lgkmcnt(0)
	s_waitcnt vmcnt(0)
	s_branch .LBB0_1181
.LpeelD:
	s_add_u32 s10, s8, 0x100
	s_addc_u32 s11, s9, 0
	s_add_i32 s41, 0, 0x10000
	s_cmp_eq_u32 s40, 40
	s_cselect_b32 s79, s1, s11
	s_cselect_b32 s78, s0, s10
	v_add_u32_e32 v152, s41, v162
	s_cselect_b32 s13, s25, s39
	s_cselect_b32 s12, s24, s38
	s_add_i32 s44, 0, 0x14000
	ds_read_b128 v[144:147], v152
	ds_read_b128 v[148:151], v152 offset:1024
	ds_read_b128 v[166:169], v152 offset:2048
	ds_read_b128 v[170:173], v152 offset:3072
	v_add_u32_e32 v152, s44, v162
	ds_read_b128 v[174:177], v152
	ds_read_b128 v[178:181], v152 offset:1024
	ds_read_b128 v[182:185], v152 offset:2048
	ds_read_b128 v[186:189], v152 offset:3072
	v_lshl_add_u64 v[152:153], s[8:9], 0, v[140:141]
	s_add_i32 m0, s89, 0xc000
	ds_read_b128 v[190:193], v164
	ds_read_b128 v[194:197], v164 offset:1024
	ds_read_b128 v[198:201], v164 offset:2048
	ds_read_b128 v[202:205], v164 offset:3072
	ds_read_b128 v[206:209], v164 offset:4096
	ds_read_b128 v[210:213], v164 offset:5120
	ds_read_b128 v[214:217], v164 offset:6144
	ds_read_b128 v[236:239], v164 offset:7168
	global_load_lds_dwordx4 v[152:153], off
	v_lshl_add_u64 v[152:153], s[8:9], 0, v[142:143]
	s_add_i32 m0, s89, 0xe000
	s_nop 0
	global_load_lds_dwordx4 v[152:153], off
	s_waitcnt vmcnt(8)
	s_waitcnt lgkmcnt(0)
	s_barrier
	s_setprio 1
	s_waitcnt lgkmcnt(0)
	v_mfma_f32_16x16x32_bf16 v[130:133], v[144:147], v[190:193], 0
	v_mfma_f32_16x16x32_bf16 v[126:129], v[166:169], v[190:193], 0
	v_mfma_f32_16x16x32_bf16 v[114:117], v[144:147], v[198:201], 0
	v_mfma_f32_16x16x32_bf16 v[110:113], v[166:169], v[198:201], 0
	v_mfma_f32_16x16x32_bf16 v[98:101], v[144:147], v[206:209], 0
	v_mfma_f32_16x16x32_bf16 v[94:97], v[166:169], v[206:209], 0
	v_mfma_f32_16x16x32_bf16 v[82:85], v[144:147], v[214:217], 0
	v_mfma_f32_16x16x32_bf16 v[78:81], v[166:169], v[214:217], 0
	v_mfma_f32_16x16x32_bf16 v[130:133], v[148:151], v[194:197], v[130:133]
	v_mfma_f32_16x16x32_bf16 v[126:129], v[170:173], v[194:197], v[126:129]
	v_mfma_f32_16x16x32_bf16 v[114:117], v[148:151], v[202:205], v[114:117]
	v_mfma_f32_16x16x32_bf16 v[110:113], v[170:173], v[202:205], v[110:113]
	v_mfma_f32_16x16x32_bf16 v[98:101], v[148:151], v[210:213], v[98:101]
	v_mfma_f32_16x16x32_bf16 v[94:97], v[170:173], v[210:213], v[94:97]
	v_mfma_f32_16x16x32_bf16 v[82:85], v[148:151], v[236:239], v[82:85]
	v_mfma_f32_16x16x32_bf16 v[78:81], v[170:173], v[236:239], v[78:81]
	s_setprio 0
	s_setprio 1
	v_mfma_f32_16x16x32_bf16 v[122:125], v[174:177], v[190:193], 0
	v_mfma_f32_16x16x32_bf16 v[118:121], v[182:185], v[190:193], 0
	v_mfma_f32_16x16x32_bf16 v[106:109], v[174:177], v[198:201], 0
	v_mfma_f32_16x16x32_bf16 v[102:105], v[182:185], v[198:201], 0
	v_mfma_f32_16x16x32_bf16 v[90:93], v[174:177], v[206:209], 0
	v_mfma_f32_16x16x32_bf16 v[86:89], v[182:185], v[206:209], 0
	v_mfma_f32_16x16x32_bf16 v[74:77], v[174:177], v[214:217], 0
	v_mfma_f32_16x16x32_bf16 v[70:73], v[182:185], v[214:217], 0
	v_mfma_f32_16x16x32_bf16 v[122:125], v[178:181], v[194:197], v[122:125]
	v_mfma_f32_16x16x32_bf16 v[118:121], v[186:189], v[194:197], v[118:121]
	v_mfma_f32_16x16x32_bf16 v[106:109], v[178:181], v[202:205], v[106:109]
	v_mfma_f32_16x16x32_bf16 v[102:105], v[186:189], v[202:205], v[102:105]
	v_mfma_f32_16x16x32_bf16 v[90:93], v[178:181], v[210:213], v[90:93]
	v_mfma_f32_16x16x32_bf16 v[86:89], v[186:189], v[210:213], v[86:89]
	v_mfma_f32_16x16x32_bf16 v[74:77], v[178:181], v[236:239], v[74:77]
	v_mfma_f32_16x16x32_bf16 v[70:73], v[186:189], v[236:239], v[70:73]
	s_setprio 0
	s_barrier
	s_add_i32 s8, s41, s88
	v_lshl_add_u64 v[152:153], s[12:13], 0, v[156:157]
	s_mov_b32 m0, s8
	ds_read_b128 v[190:193], v164 offset:16384
	ds_read_b128 v[194:197], v164 offset:17408
	ds_read_b128 v[198:201], v164 offset:18432
	ds_read_b128 v[202:205], v164 offset:19456
	ds_read_b128 v[206:209], v164 offset:20480
	ds_read_b128 v[210:213], v164 offset:21504
	ds_read_b128 v[214:217], v164 offset:22528
	ds_read_b128 v[236:239], v164 offset:23552
	global_load_lds_dwordx4 v[152:153], off
	s_add_i32 m0, s8, 0x2000
	s_add_u32 s8, s12, 0xb0000
	v_lshl_add_u64 v[218:219], s[12:13], 0, v[134:135]
	s_addc_u32 s9, s13, 0
	s_add_i32 s41, s44, s88
	global_load_lds_dwordx4 v[218:219], off
	v_lshl_add_u64 v[220:221], s[8:9], 0, v[156:157]
	s_mov_b32 m0, s41
	v_lshl_add_u64 v[222:223], s[78:79], 0, v[136:137]
	global_load_lds_dwordx4 v[220:221], off
	v_lshl_add_u64 v[220:221], s[8:9], 0, v[134:135]
	s_add_i32 m0, s41, 0x2000
	s_nop 0
	global_load_lds_dwordx4 v[220:221], off
	v_lshl_add_u64 v[220:221], s[78:79], 0, v[138:139]
	s_mov_b32 m0, s89
	s_nop 0
	global_load_lds_dwordx4 v[220:221], off
	s_mov_b32 m0, s90
	s_nop 0
	global_load_lds_dwordx4 v[222:223], off
	s_waitcnt vmcnt(8)
	s_waitcnt lgkmcnt(0)
	s_barrier
	s_setprio 1
	s_waitcnt lgkmcnt(0)
	v_mfma_f32_16x16x32_bf16 v[66:69], v[144:147], v[190:193], 0
	v_mfma_f32_16x16x32_bf16 v[62:65], v[166:169], v[190:193], 0
	v_mfma_f32_16x16x32_bf16 v[50:53], v[144:147], v[198:201], 0
	v_mfma_f32_16x16x32_bf16 v[46:49], v[166:169], v[198:201], 0
	v_mfma_f32_16x16x32_bf16 v[34:37], v[144:147], v[206:209], 0
	v_mfma_f32_16x16x32_bf16 v[30:33], v[166:169], v[206:209], 0
	v_mfma_f32_16x16x32_bf16 v[18:21], v[144:147], v[214:217], 0
	v_mfma_f32_16x16x32_bf16 v[14:17], v[166:169], v[214:217], 0
	v_mfma_f32_16x16x32_bf16 v[66:69], v[148:151], v[194:197], v[66:69]
	v_mfma_f32_16x16x32_bf16 v[62:65], v[170:173], v[194:197], v[62:65]
	v_mfma_f32_16x16x32_bf16 v[50:53], v[148:151], v[202:205], v[50:53]
	v_mfma_f32_16x16x32_bf16 v[46:49], v[170:173], v[202:205], v[46:49]
	v_mfma_f32_16x16x32_bf16 v[34:37], v[148:151], v[210:213], v[34:37]
	v_mfma_f32_16x16x32_bf16 v[30:33], v[170:173], v[210:213], v[30:33]
	v_mfma_f32_16x16x32_bf16 v[18:21], v[148:151], v[236:239], v[18:21]
	v_mfma_f32_16x16x32_bf16 v[14:17], v[170:173], v[236:239], v[14:17]
	s_setprio 0
	s_setprio 1
	v_mfma_f32_16x16x32_bf16 v[58:61], v[174:177], v[190:193], 0
	v_mfma_f32_16x16x32_bf16 v[54:57], v[182:185], v[190:193], 0
	v_mfma_f32_16x16x32_bf16 v[42:45], v[174:177], v[198:201], 0
	v_mfma_f32_16x16x32_bf16 v[38:41], v[182:185], v[198:201], 0
	v_mfma_f32_16x16x32_bf16 v[26:29], v[174:177], v[206:209], 0
	v_mfma_f32_16x16x32_bf16 v[22:25], v[182:185], v[206:209], 0
	v_mfma_f32_16x16x32_bf16 v[10:13], v[174:177], v[214:217], 0
	v_mfma_f32_16x16x32_bf16 v[6:9], v[182:185], v[214:217], 0
	v_mfma_f32_16x16x32_bf16 v[58:61], v[178:181], v[194:197], v[58:61]
	v_mfma_f32_16x16x32_bf16 v[54:57], v[186:189], v[194:197], v[54:57]
	v_mfma_f32_16x16x32_bf16 v[42:45], v[178:181], v[202:205], v[42:45]
	v_mfma_f32_16x16x32_bf16 v[38:41], v[186:189], v[202:205], v[38:41]
	v_mfma_f32_16x16x32_bf16 v[26:29], v[178:181], v[210:213], v[26:29]
	v_mfma_f32_16x16x32_bf16 v[22:25], v[186:189], v[210:213], v[22:25]
	v_mfma_f32_16x16x32_bf16 v[10:13], v[178:181], v[236:239], v[10:13]
	v_mfma_f32_16x16x32_bf16 v[6:9], v[186:189], v[236:239], v[6:9]
	s_setprio 0
	s_barrier
	s_branch .LpeelD_mid
; #define PG8_STAGE(bufoff, gbase, voff) do { _Pragma("unroll") for (int _i = 0; _i < 2; ++_i) \
;         __builtin_amdgcn_global_load_lds((const unsigned*)((const char*)(gbase) + (voff)[_i]), (PG8_LAS unsigned*)(lds + (bufoff) + ldsw + _i * 8192), 16, 0, 0); } while (0)
; #define PG8_LDA(dst, b, h) do { _Pragma("unroll") for (int m = 0; m < 4; ++m) _Pragma("unroll") for (int k = 0; k < 2; ++k) dst[m][k] = *(const PG8_LAS bf16x8*)(lds + PG8_SA(b, h) + aoff + m * 2048 + k * 1024); } while (0)
; #define PG8_LDB(dst, b, h) do { _Pragma("unroll") for (int n = 0; n < 2; ++n) _Pragma("unroll") for (int k = 0; k < 2; ++k) dst[n][k] = *(const PG8_LAS bf16x8*)(lds + PG8_SB(b, h) + boff + n * 2048 + k * 1024); } while (0)
; #define PG8_MMA(ai, bj, At, Bt) do { __builtin_amdgcn_s_setprio(1); _Pragma("unroll") for (int m = 0; m < 4; ++m) _Pragma("unroll") for (int n = 0; n < 2; ++n) _Pragma("unroll") for (int k = 0; k < 2; ++k) \
;         acc[ai][bj][m][n] = __builtin_amdgcn_mfma_f32_16x16x32_bf16(Bt[n][k], At[m][k], acc[ai][bj][m][n], 0, 0, 0); __builtin_amdgcn_s_setprio(0); } while (0)
; #define PG8_WAIT_V(n) asm volatile("s_waitcnt vmcnt(" #n ")" ::: "memory")
; #define PG8_WAIT_L(n) asm volatile("s_waitcnt lgkmcnt(" #n ")" ::: "memory")
; #define PG8_BAR __builtin_amdgcn_s_barrier()
; #define PG8_SCHED __builtin_amdgcn_sched_barrier(0)
; template <class Epi, class Sched, bool ALIGN_EPI = false, bool SP2 = false>
; __device__ __forceinline__ void gemm_phase(PG8_LAS unsigned char* lds, const Gemm g, const Sched& S, const Epi& E) {
;     ...
;             PG8_LDB(B0, 0, 0); PG8_LDB(B1, 0, 1); PG8_SCHED; PG8_LDA(At, 0, 0); PG8_STAGE(PG8_SA(1, 1), a1 + hstep, voffA);
;             PG8_WAIT_V(8); PG8_WAIT_L(0); PG8_BAR; PG8_MMA(0, 0, At, B0); PG8_MMA(0, 1, At, B1); PG8_BAR; PG8_SCHED;
;             PG8_LDA(At, 0, 1); PG8_STAGE(PG8_SB(0, 0), b2, voffB); PG8_STAGE(PG8_SB(0, 1), b2 + hstep, voffB); PG8_STAGE(PG8_SA(0, 0), a2, voffA);
;             PG8_WAIT_V(8); PG8_WAIT_L(0); PG8_BAR; PG8_MMA(1, 0, At, B0); PG8_MMA(1, 1, At, B1); PG8_BAR; PG8_SCHED;
.LBB0_1181:
	s_cmp_eq_u32 s40, -2
	s_cbranch_scc1 .LpeelD
	s_add_u32 s10, s8, 0x100
	s_addc_u32 s11, s9, 0
	s_add_i32 s41, 0, 0x10000
	s_cmp_eq_u32 s40, 40
	s_cselect_b32 s79, s1, s11
	s_cselect_b32 s78, s0, s10
	v_add_u32_e32 v152, s41, v162
	s_cselect_b32 s13, s25, s39
	s_cselect_b32 s12, s24, s38
	s_add_i32 s44, 0, 0x14000
	ds_read_b128 v[144:147], v152
	ds_read_b128 v[148:151], v152 offset:1024
	ds_read_b128 v[166:169], v152 offset:2048
	ds_read_b128 v[170:173], v152 offset:3072
	v_add_u32_e32 v152, s44, v162
	ds_read_b128 v[174:177], v152
	ds_read_b128 v[178:181], v152 offset:1024
	ds_read_b128 v[182:185], v152 offset:2048
	ds_read_b128 v[186:189], v152 offset:3072
	v_lshl_add_u64 v[152:153], s[8:9], 0, v[140:141]
	s_add_i32 m0, s89, 0xc000
	ds_read_b128 v[190:193], v164
	ds_read_b128 v[194:197], v164 offset:1024
	ds_read_b128 v[198:201], v164 offset:2048
	ds_read_b128 v[202:205], v164 offset:3072
	ds_read_b128 v[206:209], v164 offset:4096
	ds_read_b128 v[210:213], v164 offset:5120
	ds_read_b128 v[214:217], v164 offset:6144
	ds_read_b128 v[236:239], v164 offset:7168
	global_load_lds_dwordx4 v[152:153], off
	v_lshl_add_u64 v[152:153], s[8:9], 0, v[142:143]
	s_add_i32 m0, s89, 0xe000
	s_nop 0
	global_load_lds_dwordx4 v[152:153], off
	s_waitcnt vmcnt(8)
	s_waitcnt lgkmcnt(0)
	s_barrier
	s_setprio 1
	s_waitcnt lgkmcnt(0)
	v_mfma_f32_16x16x32_bf16 v[130:133], v[144:147], v[190:193], v[130:133]
	v_mfma_f32_16x16x32_bf16 v[126:129], v[166:169], v[190:193], v[126:129]
	v_mfma_f32_16x16x32_bf16 v[114:117], v[144:147], v[198:201], v[114:117]
	v_mfma_f32_16x16x32_bf16 v[110:113], v[166:169], v[198:201], v[110:113]
	v_mfma_f32_16x16x32_bf16 v[98:101], v[144:147], v[206:209], v[98:101]
	v_mfma_f32_16x16x32_bf16 v[94:97], v[166:169], v[206:209], v[94:97]
	v_mfma_f32_16x16x32_bf16 v[82:85], v[144:147], v[214:217], v[82:85]
	v_mfma_f32_16x16x32_bf16 v[78:81], v[166:169], v[214:217], v[78:81]
	v_mfma_f32_16x16x32_bf16 v[130:133], v[148:151], v[194:197], v[130:133]
	v_mfma_f32_16x16x32_bf16 v[126:129], v[170:173], v[194:197], v[126:129]
	v_mfma_f32_16x16x32_bf16 v[114:117], v[148:151], v[202:205], v[114:117]
	v_mfma_f32_16x16x32_bf16 v[110:113], v[170:173], v[202:205], v[110:113]
	v_mfma_f32_16x16x32_bf16 v[98:101], v[148:151], v[210:213], v[98:101]
	v_mfma_f32_16x16x32_bf16 v[94:97], v[170:173], v[210:213], v[94:97]
	v_mfma_f32_16x16x32_bf16 v[82:85], v[148:151], v[236:239], v[82:85]
	v_mfma_f32_16x16x32_bf16 v[78:81], v[170:173], v[236:239], v[78:81]
	s_setprio 0
	s_setprio 1
	v_mfma_f32_16x16x32_bf16 v[122:125], v[174:177], v[190:193], v[122:125]
	v_mfma_f32_16x16x32_bf16 v[118:121], v[182:185], v[190:193], v[118:121]
	v_mfma_f32_16x16x32_bf16 v[106:109], v[174:177], v[198:201], v[106:109]
	v_mfma_f32_16x16x32_bf16 v[102:105], v[182:185], v[198:201], v[102:105]
	v_mfma_f32_16x16x32_bf16 v[90:93], v[174:177], v[206:209], v[90:93]
	v_mfma_f32_16x16x32_bf16 v[86:89], v[182:185], v[206:209], v[86:89]
	v_mfma_f32_16x16x32_bf16 v[74:77], v[174:177], v[214:217], v[74:77]
	v_mfma_f32_16x16x32_bf16 v[70:73], v[182:185], v[214:217], v[70:73]
	v_mfma_f32_16x16x32_bf16 v[122:125], v[178:181], v[194:197], v[122:125]
	v_mfma_f32_16x16x32_bf16 v[118:121], v[186:189], v[194:197], v[118:121]
	v_mfma_f32_16x16x32_bf16 v[106:109], v[178:181], v[202:205], v[106:109]
	v_mfma_f32_16x16x32_bf16 v[102:105], v[186:189], v[202:205], v[102:105]
	v_mfma_f32_16x16x32_bf16 v[90:93], v[178:181], v[210:213], v[90:93]
	v_mfma_f32_16x16x32_bf16 v[86:89], v[186:189], v[210:213], v[86:89]
	v_mfma_f32_16x16x32_bf16 v[74:77], v[178:181], v[236:239], v[74:77]
	v_mfma_f32_16x16x32_bf16 v[70:73], v[186:189], v[236:239], v[70:73]
	s_setprio 0
	s_barrier
	s_add_i32 s8, s41, s88
	v_lshl_add_u64 v[152:153], s[12:13], 0, v[156:157]
	s_mov_b32 m0, s8
	ds_read_b128 v[190:193], v164 offset:16384
	ds_read_b128 v[194:197], v164 offset:17408
	ds_read_b128 v[198:201], v164 offset:18432
	ds_read_b128 v[202:205], v164 offset:19456
	ds_read_b128 v[206:209], v164 offset:20480
	ds_read_b128 v[210:213], v164 offset:21504
	ds_read_b128 v[214:217], v164 offset:22528
	ds_read_b128 v[236:239], v164 offset:23552
	global_load_lds_dwordx4 v[152:153], off
	s_add_i32 m0, s8, 0x2000
	s_add_u32 s8, s12, 0xb0000
	v_lshl_add_u64 v[218:219], s[12:13], 0, v[134:135]
	s_addc_u32 s9, s13, 0
	s_add_i32 s41, s44, s88
	global_load_lds_dwordx4 v[218:219], off
	v_lshl_add_u64 v[220:221], s[8:9], 0, v[156:157]
	s_mov_b32 m0, s41
	v_lshl_add_u64 v[222:223], s[78:79], 0, v[136:137]
	global_load_lds_dwordx4 v[220:221], off
	v_lshl_add_u64 v[220:221], s[8:9], 0, v[134:135]
	s_add_i32 m0, s41, 0x2000
	s_nop 0
	global_load_lds_dwordx4 v[220:221], off
	v_lshl_add_u64 v[220:221], s[78:79], 0, v[138:139]
	s_mov_b32 m0, s89
	s_nop 0
	global_load_lds_dwordx4 v[220:221], off
	s_mov_b32 m0, s90
	s_nop 0
	global_load_lds_dwordx4 v[222:223], off
	s_waitcnt vmcnt(8)
	s_waitcnt lgkmcnt(0)
	s_barrier
; #define PG8_STAGE(bufoff, gbase, voff) do { _Pragma("unroll") for (int _i = 0; _i < 2; ++_i) \
;         __builtin_amdgcn_global_load_lds((const unsigned*)((const char*)(gbase) + (voff)[_i]), (PG8_LAS unsigned*)(lds + (bufoff) + ldsw + _i * 8192), 16, 0, 0); } while (0)
; #define PG8_LDA(dst, b, h) do { _Pragma("unroll") for (int m = 0; m < 4; ++m) _Pragma("unroll") for (int k = 0; k < 2; ++k) dst[m][k] = *(const PG8_LAS bf16x8*)(lds + PG8_SA(b, h) + aoff + m * 2048 + k * 1024); } while (0)
; #define PG8_LDB(dst, b, h) do { _Pragma("unroll") for (int n = 0; n < 2; ++n) _Pragma("unroll") for (int k = 0; k < 2; ++k) dst[n][k] = *(const PG8_LAS bf16x8*)(lds + PG8_SB(b, h) + boff + n * 2048 + k * 1024); } while (0)
; #define PG8_MMA(ai, bj, At, Bt) do { __builtin_amdgcn_s_setprio(1); _Pragma("unroll") for (int m = 0; m < 4; ++m) _Pragma("unroll") for (int n = 0; n < 2; ++n) _Pragma("unroll") for (int k = 0; k < 2; ++k) \
;         acc[ai][bj][m][n] = __builtin_amdgcn_mfma_f32_16x16x32_bf16(Bt[n][k], At[m][k], acc[ai][bj][m][n], 0, 0, 0); __builtin_amdgcn_s_setprio(0); } while (0)
; #define PG8_WAIT_V(n) asm volatile("s_waitcnt vmcnt(" #n ")" ::: "memory")
; #define PG8_WAIT_L(n) asm volatile("s_waitcnt lgkmcnt(" #n ")" ::: "memory")
; #define PG8_BAR __builtin_amdgcn_s_barrier()
; #define PG8_SCHED __builtin_amdgcn_sched_barrier(0)
; template <class Epi, class Sched, bool ALIGN_EPI = false, bool SP2 = false>
; __device__ __forceinline__ void gemm_phase(PG8_LAS unsigned char* lds, const Gemm g, const Sched& S, const Epi& E) {
;     ...
;             PG8_WAIT_V(8); PG8_WAIT_L(0); PG8_BAR; PG8_MMA(1, 0, At, B0); PG8_MMA(1, 1, At, B1); PG8_BAR; PG8_SCHED;
;             PG8_LDB(B0, 1, 0); PG8_LDB(B1, 1, 1); PG8_SCHED; PG8_LDA(At, 1, 0); PG8_STAGE(PG8_SA(0, 1), a2 + hstep, voffA);
;             PG8_WAIT_V(8); PG8_WAIT_L(0); PG8_BAR; PG8_MMA(0, 0, At, B0); PG8_MMA(0, 1, At, B1); PG8_BAR; PG8_SCHED;
	s_setprio 1
	s_waitcnt lgkmcnt(0)
	v_mfma_f32_16x16x32_bf16 v[66:69], v[144:147], v[190:193], v[66:69]
	v_mfma_f32_16x16x32_bf16 v[62:65], v[166:169], v[190:193], v[62:65]
	v_mfma_f32_16x16x32_bf16 v[50:53], v[144:147], v[198:201], v[50:53]
	v_mfma_f32_16x16x32_bf16 v[46:49], v[166:169], v[198:201], v[46:49]
	v_mfma_f32_16x16x32_bf16 v[34:37], v[144:147], v[206:209], v[34:37]
	v_mfma_f32_16x16x32_bf16 v[30:33], v[166:169], v[206:209], v[30:33]
	v_mfma_f32_16x16x32_bf16 v[18:21], v[144:147], v[214:217], v[18:21]
	v_mfma_f32_16x16x32_bf16 v[14:17], v[166:169], v[214:217], v[14:17]
	v_mfma_f32_16x16x32_bf16 v[66:69], v[148:151], v[194:197], v[66:69]
	v_mfma_f32_16x16x32_bf16 v[62:65], v[170:173], v[194:197], v[62:65]
	v_mfma_f32_16x16x32_bf16 v[50:53], v[148:151], v[202:205], v[50:53]
	v_mfma_f32_16x16x32_bf16 v[46:49], v[170:173], v[202:205], v[46:49]
	v_mfma_f32_16x16x32_bf16 v[34:37], v[148:151], v[210:213], v[34:37]
	v_mfma_f32_16x16x32_bf16 v[30:33], v[170:173], v[210:213], v[30:33]
	v_mfma_f32_16x16x32_bf16 v[18:21], v[148:151], v[236:239], v[18:21]
	v_mfma_f32_16x16x32_bf16 v[14:17], v[170:173], v[236:239], v[14:17]
	s_setprio 0
	s_setprio 1
	v_mfma_f32_16x16x32_bf16 v[58:61], v[174:177], v[190:193], v[58:61]
	v_mfma_f32_16x16x32_bf16 v[54:57], v[182:185], v[190:193], v[54:57]
	v_mfma_f32_16x16x32_bf16 v[42:45], v[174:177], v[198:201], v[42:45]
	v_mfma_f32_16x16x32_bf16 v[38:41], v[182:185], v[198:201], v[38:41]
	v_mfma_f32_16x16x32_bf16 v[26:29], v[174:177], v[206:209], v[26:29]
	v_mfma_f32_16x16x32_bf16 v[22:25], v[182:185], v[206:209], v[22:25]
	v_mfma_f32_16x16x32_bf16 v[10:13], v[174:177], v[214:217], v[10:13]
	v_mfma_f32_16x16x32_bf16 v[6:9], v[182:185], v[214:217], v[6:9]
	v_mfma_f32_16x16x32_bf16 v[58:61], v[178:181], v[194:197], v[58:61]
	v_mfma_f32_16x16x32_bf16 v[54:57], v[186:189], v[194:197], v[54:57]
	v_mfma_f32_16x16x32_bf16 v[42:45], v[178:181], v[202:205], v[42:45]
	v_mfma_f32_16x16x32_bf16 v[38:41], v[186:189], v[202:205], v[38:41]
	v_mfma_f32_16x16x32_bf16 v[26:29], v[178:181], v[210:213], v[26:29]
	v_mfma_f32_16x16x32_bf16 v[22:25], v[186:189], v[210:213], v[22:25]
	v_mfma_f32_16x16x32_bf16 v[10:13], v[178:181], v[236:239], v[10:13]
	v_mfma_f32_16x16x32_bf16 v[6:9], v[186:189], v[236:239], v[6:9]
	s_setprio 0
	s_barrier
.LpeelD_mid:
	s_add_i32 s41, 0, 0x18000
	v_add_u32_e32 v165, s41, v162
	s_add_i32 s44, 0, 0x1c000
	ds_read_b128 v[144:147], v165
	ds_read_b128 v[148:151], v165 offset:1024
	ds_read_b128 v[166:169], v165 offset:2048
	ds_read_b128 v[170:173], v165 offset:3072
	v_add_u32_e32 v165, s44, v162
	ds_read_b128 v[174:177], v165
	ds_read_b128 v[178:181], v165 offset:1024
	ds_read_b128 v[182:185], v165 offset:2048
	ds_read_b128 v[186:189], v165 offset:3072
	s_add_u32 s8, s78, 0xb0000
	s_addc_u32 s9, s79, 0
	s_mov_b32 m0, s91
	v_lshl_add_u64 v[226:227], s[8:9], 0, v[138:139]
	ds_read_b128 v[190:193], v164 offset:32768
	ds_read_b128 v[194:197], v164 offset:33792
	ds_read_b128 v[198:201], v164 offset:34816
	ds_read_b128 v[202:205], v164 offset:35840
	ds_read_b128 v[206:209], v164 offset:36864
	ds_read_b128 v[210:213], v164 offset:37888
	ds_read_b128 v[214:217], v164 offset:38912
	ds_read_b128 v[236:239], v164 offset:39936
	global_load_lds_dwordx4 v[226:227], off
	v_lshl_add_u64 v[226:227], s[8:9], 0, v[136:137]
	s_mov_b32 m0, s92
	s_nop 0
	global_load_lds_dwordx4 v[226:227], off
	s_waitcnt vmcnt(8)
	s_waitcnt lgkmcnt(0)
	s_barrier
	s_setprio 1
	s_waitcnt lgkmcnt(0)
	v_mfma_f32_16x16x32_bf16 v[130:133], v[144:147], v[190:193], v[130:133]
	v_mfma_f32_16x16x32_bf16 v[126:129], v[166:169], v[190:193], v[126:129]
	v_mfma_f32_16x16x32_bf16 v[114:117], v[144:147], v[198:201], v[114:117]
	v_mfma_f32_16x16x32_bf16 v[110:113], v[166:169], v[198:201], v[110:113]
	v_mfma_f32_16x16x32_bf16 v[98:101], v[144:147], v[206:209], v[98:101]
	v_mfma_f32_16x16x32_bf16 v[94:97], v[166:169], v[206:209], v[94:97]
	v_mfma_f32_16x16x32_bf16 v[82:85], v[144:147], v[214:217], v[82:85]
	v_mfma_f32_16x16x32_bf16 v[78:81], v[166:169], v[214:217], v[78:81]
	v_mfma_f32_16x16x32_bf16 v[130:133], v[148:151], v[194:197], v[130:133]
	v_mfma_f32_16x16x32_bf16 v[126:129], v[170:173], v[194:197], v[126:129]
	v_mfma_f32_16x16x32_bf16 v[114:117], v[148:151], v[202:205], v[114:117]
	v_mfma_f32_16x16x32_bf16 v[110:113], v[170:173], v[202:205], v[110:113]
	v_mfma_f32_16x16x32_bf16 v[98:101], v[148:151], v[210:213], v[98:101]
	v_mfma_f32_16x16x32_bf16 v[94:97], v[170:173], v[210:213], v[94:97]
	v_mfma_f32_16x16x32_bf16 v[82:85], v[148:151], v[236:239], v[82:85]
	v_mfma_f32_16x16x32_bf16 v[78:81], v[170:173], v[236:239], v[78:81]
	s_setprio 0
	s_setprio 1
	v_mfma_f32_16x16x32_bf16 v[122:125], v[174:177], v[190:193], v[122:125]
	v_mfma_f32_16x16x32_bf16 v[118:121], v[182:185], v[190:193], v[118:121]
	v_mfma_f32_16x16x32_bf16 v[106:109], v[174:177], v[198:201], v[106:109]
	v_mfma_f32_16x16x32_bf16 v[102:105], v[182:185], v[198:201], v[102:105]
	v_mfma_f32_16x16x32_bf16 v[90:93], v[174:177], v[206:209], v[90:93]
	v_mfma_f32_16x16x32_bf16 v[86:89], v[182:185], v[206:209], v[86:89]
	v_mfma_f32_16x16x32_bf16 v[74:77], v[174:177], v[214:217], v[74:77]
	v_mfma_f32_16x16x32_bf16 v[70:73], v[182:185], v[214:217], v[70:73]
	v_mfma_f32_16x16x32_bf16 v[122:125], v[178:181], v[194:197], v[122:125]
	v_mfma_f32_16x16x32_bf16 v[118:121], v[186:189], v[194:197], v[118:121]
	v_mfma_f32_16x16x32_bf16 v[106:109], v[178:181], v[202:205], v[106:109]
	v_mfma_f32_16x16x32_bf16 v[102:105], v[186:189], v[202:205], v[102:105]
	v_mfma_f32_16x16x32_bf16 v[90:93], v[178:181], v[210:213], v[90:93]
	v_mfma_f32_16x16x32_bf16 v[86:89], v[186:189], v[210:213], v[86:89]
	v_mfma_f32_16x16x32_bf16 v[74:77], v[178:181], v[236:239], v[74:77]
	v_mfma_f32_16x16x32_bf16 v[70:73], v[186:189], v[236:239], v[70:73]
	s_setprio 0
	s_barrier
; #define PG8_STAGE(bufoff, gbase, voff) do { _Pragma("unroll") for (int _i = 0; _i < 2; ++_i) \
;         __builtin_amdgcn_global_load_lds((const unsigned*)((const char*)(gbase) + (voff)[_i]), (PG8_LAS unsigned*)(lds + (bufoff) + ldsw + _i * 8192), 16, 0, 0); } while (0)
; #define PG8_LDA(dst, b, h) do { _Pragma("unroll") for (int m = 0; m < 4; ++m) _Pragma("unroll") for (int k = 0; k < 2; ++k) dst[m][k] = *(const PG8_LAS bf16x8*)(lds + PG8_SA(b, h) + aoff + m * 2048 + k * 1024); } while (0)
; #define PG8_MMA(ai, bj, At, Bt) do { __builtin_amdgcn_s_setprio(1); _Pragma("unroll") for (int m = 0; m < 4; ++m) _Pragma("unroll") for (int n = 0; n < 2; ++n) _Pragma("unroll") for (int k = 0; k < 2; ++k) \
;         acc[ai][bj][m][n] = __builtin_amdgcn_mfma_f32_16x16x32_bf16(Bt[n][k], At[m][k], acc[ai][bj][m][n], 0, 0, 0); __builtin_amdgcn_s_setprio(0); } while (0)
; #define PG8_WAIT_V(n) asm volatile("s_waitcnt vmcnt(" #n ")" ::: "memory")
; #define PG8_WAIT_L(n) asm volatile("s_waitcnt lgkmcnt(" #n ")" ::: "memory")
; #define PG8_BAR __builtin_amdgcn_s_barrier()
; #define PG8_SCHED __builtin_amdgcn_sched_barrier(0)
; template <class Epi, class Sched, bool ALIGN_EPI = false, bool SP2 = false>
; __device__ __forceinline__ void gemm_phase(PG8_LAS unsigned char* lds, const Gemm g, const Sched& S, const Epi& E) {
;     ...
;             PG8_LDA(At, 1, 1); PG8_STAGE(PG8_SB(1, 0), b3, voffB); PG8_STAGE(PG8_SB(1, 1), b3 + hstep, voffB); PG8_STAGE(PG8_SA(1, 0), a3, voffA);
;             PG8_WAIT_V(8); PG8_WAIT_L(0); PG8_BAR; PG8_MMA(1, 0, At, B0); PG8_MMA(1, 1, At, B1); PG8_BAR; PG8_SCHED;
	s_add_i32 s8, s41, s88
	v_lshl_add_u64 v[152:153], v[152:153], 0, s[68:69]
	s_mov_b32 m0, s8
	ds_read_b128 v[190:193], v164 offset:49152
	ds_read_b128 v[194:197], v164 offset:50176
	ds_read_b128 v[198:201], v164 offset:51200
	ds_read_b128 v[202:205], v164 offset:52224
	ds_read_b128 v[206:209], v164 offset:53248
	ds_read_b128 v[210:213], v164 offset:54272
	ds_read_b128 v[214:217], v164 offset:55296
	ds_read_b128 v[236:239], v164 offset:56320
	global_load_lds_dwordx4 v[152:153], off
	s_add_i32 m0, s8, 0x2000
	s_add_u32 s8, s12, 0xb0080
	v_lshl_add_u64 v[152:153], v[218:219], 0, s[68:69]
	s_addc_u32 s9, s13, 0
	s_add_i32 s12, s44, s88
	global_load_lds_dwordx4 v[152:153], off
	v_lshl_add_u64 v[152:153], s[8:9], 0, v[156:157]
	s_mov_b32 m0, s12
	s_nop 0
	global_load_lds_dwordx4 v[152:153], off
	v_lshl_add_u64 v[152:153], s[8:9], 0, v[134:135]
	s_add_i32 m0, s12, 0x2000
	s_nop 0
	global_load_lds_dwordx4 v[152:153], off
	v_lshl_add_u64 v[152:153], v[220:221], 0, s[68:69]
	s_mov_b32 m0, s93
	s_nop 0
	global_load_lds_dwordx4 v[152:153], off
	v_lshl_add_u64 v[152:153], v[222:223], 0, s[68:69]
	s_mov_b32 m0, s19
	s_nop 0
	global_load_lds_dwordx4 v[152:153], off
	s_waitcnt vmcnt(8)
	s_waitcnt lgkmcnt(0)
	s_barrier
	s_setprio 1
	s_waitcnt lgkmcnt(0)
	v_mfma_f32_16x16x32_bf16 v[66:69], v[144:147], v[190:193], v[66:69]
	v_mfma_f32_16x16x32_bf16 v[62:65], v[166:169], v[190:193], v[62:65]
	v_mfma_f32_16x16x32_bf16 v[50:53], v[144:147], v[198:201], v[50:53]
	v_mfma_f32_16x16x32_bf16 v[46:49], v[166:169], v[198:201], v[46:49]
	v_mfma_f32_16x16x32_bf16 v[34:37], v[144:147], v[206:209], v[34:37]
	v_mfma_f32_16x16x32_bf16 v[30:33], v[166:169], v[206:209], v[30:33]
	v_mfma_f32_16x16x32_bf16 v[18:21], v[144:147], v[214:217], v[18:21]
	v_mfma_f32_16x16x32_bf16 v[14:17], v[166:169], v[214:217], v[14:17]
	v_mfma_f32_16x16x32_bf16 v[66:69], v[148:151], v[194:197], v[66:69]
	v_mfma_f32_16x16x32_bf16 v[62:65], v[170:173], v[194:197], v[62:65]
	v_mfma_f32_16x16x32_bf16 v[50:53], v[148:151], v[202:205], v[50:53]
	v_mfma_f32_16x16x32_bf16 v[46:49], v[170:173], v[202:205], v[46:49]
	v_mfma_f32_16x16x32_bf16 v[34:37], v[148:151], v[210:213], v[34:37]
	v_mfma_f32_16x16x32_bf16 v[30:33], v[170:173], v[210:213], v[30:33]
	v_mfma_f32_16x16x32_bf16 v[18:21], v[148:151], v[236:239], v[18:21]
	v_mfma_f32_16x16x32_bf16 v[14:17], v[170:173], v[236:239], v[14:17]
	s_setprio 0
	s_setprio 1
	v_mfma_f32_16x16x32_bf16 v[58:61], v[174:177], v[190:193], v[58:61]
	v_mfma_f32_16x16x32_bf16 v[54:57], v[182:185], v[190:193], v[54:57]
	v_mfma_f32_16x16x32_bf16 v[42:45], v[174:177], v[198:201], v[42:45]
	v_mfma_f32_16x16x32_bf16 v[38:41], v[182:185], v[198:201], v[38:41]
	v_mfma_f32_16x16x32_bf16 v[26:29], v[174:177], v[206:209], v[26:29]
	v_mfma_f32_16x16x32_bf16 v[22:25], v[182:185], v[206:209], v[22:25]
	v_mfma_f32_16x16x32_bf16 v[10:13], v[174:177], v[214:217], v[10:13]
	v_mfma_f32_16x16x32_bf16 v[6:9], v[182:185], v[214:217], v[6:9]
	v_mfma_f32_16x16x32_bf16 v[58:61], v[178:181], v[194:197], v[58:61]
	v_mfma_f32_16x16x32_bf16 v[54:57], v[186:189], v[194:197], v[54:57]
	v_mfma_f32_16x16x32_bf16 v[42:45], v[178:181], v[202:205], v[42:45]
	v_mfma_f32_16x16x32_bf16 v[38:41], v[186:189], v[202:205], v[38:41]
	v_mfma_f32_16x16x32_bf16 v[26:29], v[178:181], v[210:213], v[26:29]
	v_mfma_f32_16x16x32_bf16 v[22:25], v[186:189], v[210:213], v[22:25]
	v_mfma_f32_16x16x32_bf16 v[10:13], v[178:181], v[236:239], v[10:13]
	v_mfma_f32_16x16x32_bf16 v[6:9], v[186:189], v[236:239], v[6:9]
	s_setprio 0
	s_barrier
	s_add_i32 s40, s40, 2
	s_add_u32 s38, s38, 0x100
	s_addc_u32 s39, s39, 0
	s_cmp_gt_u32 s40, 41
	s_mov_b64 s[8:9], s[10:11]
	s_cbranch_scc0 .LBB0_1181
	s_and_b64 vcc, exec, s[96:97]
	s_cbranch_vccz .LBB0_1184
	s_barrier
